# v34: v33 + per-cluster s_setprio flips also removed from the P3/P4/P5 K-loops
# speedup vs baseline: 1.0328x; 1.0002x over previous
; #define PG8_STAGE(bufoff, gbase, voff) do { _Pragma("unroll") for (int _i = 0; _i < 2; ++_i) \
;         __builtin_amdgcn_global_load_lds((const unsigned*)((const char*)(gbase) + (voff)[_i]), (LAS unsigned*)(lds + (bufoff) + ldsw + _i * 8192), 16, 0, 0); } while (0)
; #define PG8_LDA(dst, b, h) do { _Pragma("unroll") for (int m = 0; m < 4; ++m) _Pragma("unroll") for (int k = 0; k < 2; ++k) dst[m][k] = *(const LAS bf16x8*)(lds + PG8_SA(b, h) + aoff + m * 2048 + k * 1024); } while (0)
; #define PG8_LDB(dst, b, h) do { _Pragma("unroll") for (int n = 0; n < 2; ++n) _Pragma("unroll") for (int k = 0; k < 2; ++k) dst[n][k] = *(const LAS bf16x8*)(lds + PG8_SB(b, h) + boff + n * 2048 + k * 1024); } while (0)
; #define PG8_MMA(ai, bj, At, Bt) do { __builtin_amdgcn_s_setprio(1); _Pragma("unroll") for (int m = 0; m < 4; ++m) _Pragma("unroll") for (int n = 0; n < 2; ++n) _Pragma("unroll") for (int k = 0; k < 2; ++k) \
;         acc[ai][bj][m][n] = __builtin_amdgcn_mfma_f32_16x16x32_bf16(Bt[n][k], At[m][k], acc[ai][bj][m][n], 0, 0, 0); __builtin_amdgcn_s_setprio(0); } while (0)
; #define PG8_WAIT_V(n) asm volatile("s_waitcnt vmcnt(" #n ")" ::: "memory")
; #define PG8_WAIT_L(n) asm volatile("s_waitcnt lgkmcnt(" #n ")" ::: "memory")
; #define PG8_BAR __builtin_amdgcn_s_barrier()
; template <class Epi, int AC0, int BC0, int NT0, int AC1, int BC1, int NT1>
; __device__ __forceinline__ void gemm_phase(LAS unsigned char* lds, const Gemm g, const StaticOrder& S, const Epi& E, int tid) {
;     ...
;         for (int t = 0; t < nt; t += 2) {
;             const bool last = (t == nt - 2);
;             const char* a1 = cA + (size_t)(t + 1) * kstep;
;             const char* a2 = last ? nA : cA + (size_t)(t + 2) * kstep; const char* b2 = last ? nB : cB + (size_t)(t + 2) * kstep;
;             const char* a3 = a2 + kstep; const char* b3 = b2 + kstep;
;             PG8_LDB(B0, 0, 0); PG8_LDB(B1, 0, 1); PG8_SCHED; PG8_LDA(At, 0, 0); PG8_STAGE(PG8_SA(1, 1), a1 + hstepA, voffA);
;             PG8_WAIT_V(8); PG8_WAIT_L(0); PG8_BAR; PG8_MMA(0, 0, At, B0); PG8_MMA(0, 1, At, B1); PG8_BAR; PG8_SCHED;
;             PG8_LDA(At, 0, 1); PG8_STAGE(PG8_SB(0, 0), b2, voffB); PG8_STAGE(PG8_SB(0, 1), b2 + hstepB, voffB); PG8_STAGE(PG8_SA(0, 0), a2, voffA);
;             PG8_WAIT_V(8); PG8_WAIT_L(0); PG8_BAR; PG8_MMA(1, 0, At, B0); PG8_MMA(1, 1, At, B1); PG8_BAR; PG8_SCHED;
.LBB0_725:
	v_add_u32_e32 v142, s29, v222
	v_add_u32_e32 v158, s30, v222
	ds_read_b128 v[130:133], v142
	ds_read_b128 v[134:137], v142 offset:1024
	ds_read_b128 v[138:141], v142 offset:2048
	ds_read_b128 v[142:145], v142 offset:3072
	ds_read_b128 v[146:149], v158
	ds_read_b128 v[150:153], v158 offset:1024
	ds_read_b128 v[154:157], v158 offset:2048
	ds_read_b128 v[158:161], v158 offset:3072
	s_add_u32 s0, s14, 0x100
	s_addc_u32 s1, s15, 0
	s_cmp_eq_u32 s42, 4
	s_cselect_b32 vcc_hi, s19, s1
	s_cselect_b32 vcc_lo, s18, s0
	s_cselect_b32 s17, s3, s37
	s_cselect_b32 s16, s13, s33
	v_lshl_add_u64 v[212:213], s[14:15], 0, v[206:207]
	s_add_i32 m0, s94, 0xc000
	ds_read_b128 v[162:165], v228
	ds_read_b128 v[166:169], v228 offset:1024
	ds_read_b128 v[170:173], v228 offset:2048
	ds_read_b128 v[174:177], v228 offset:3072
	ds_read_b128 v[178:181], v228 offset:4096
	ds_read_b128 v[182:185], v228 offset:5120
	ds_read_b128 v[186:189], v228 offset:6144
	ds_read_b128 v[190:193], v228 offset:7168
	global_load_lds_dwordx4 v[212:213], off
	v_lshl_add_u64 v[212:213], s[14:15], 0, v[208:209]
	s_add_i32 m0, s94, 0xe000
	s_nop 0
	global_load_lds_dwordx4 v[212:213], off
	s_waitcnt vmcnt(8)
	s_waitcnt lgkmcnt(0)
	s_barrier
	s_waitcnt lgkmcnt(0)
	v_mfma_f32_16x16x32_bf16 v[126:129], v[130:133], v[162:165], v[126:129]
	v_mfma_f32_16x16x32_bf16 v[122:125], v[138:141], v[162:165], v[122:125]
	v_mfma_f32_16x16x32_bf16 v[118:121], v[130:133], v[170:173], v[118:121]
	v_mfma_f32_16x16x32_bf16 v[114:117], v[138:141], v[170:173], v[114:117]
	v_mfma_f32_16x16x32_bf16 v[110:113], v[130:133], v[178:181], v[110:113]
	v_mfma_f32_16x16x32_bf16 v[106:109], v[138:141], v[178:181], v[106:109]
	v_mfma_f32_16x16x32_bf16 v[102:105], v[130:133], v[186:189], v[102:105]
	v_mfma_f32_16x16x32_bf16 v[98:101], v[138:141], v[186:189], v[98:101]
	v_mfma_f32_16x16x32_bf16 v[126:129], v[134:137], v[166:169], v[126:129]
	v_mfma_f32_16x16x32_bf16 v[122:125], v[142:145], v[166:169], v[122:125]
	v_mfma_f32_16x16x32_bf16 v[118:121], v[134:137], v[174:177], v[118:121]
	v_mfma_f32_16x16x32_bf16 v[114:117], v[142:145], v[174:177], v[114:117]
	v_mfma_f32_16x16x32_bf16 v[110:113], v[134:137], v[182:185], v[110:113]
	v_mfma_f32_16x16x32_bf16 v[106:109], v[142:145], v[182:185], v[106:109]
	v_mfma_f32_16x16x32_bf16 v[102:105], v[134:137], v[190:193], v[102:105]
	v_mfma_f32_16x16x32_bf16 v[98:101], v[142:145], v[190:193], v[98:101]
	v_mfma_f32_16x16x32_bf16 v[94:97], v[146:149], v[162:165], v[94:97]
	v_mfma_f32_16x16x32_bf16 v[90:93], v[154:157], v[162:165], v[90:93]
	v_mfma_f32_16x16x32_bf16 v[86:89], v[146:149], v[170:173], v[86:89]
	v_mfma_f32_16x16x32_bf16 v[82:85], v[154:157], v[170:173], v[82:85]
	v_mfma_f32_16x16x32_bf16 v[78:81], v[146:149], v[178:181], v[78:81]
	v_mfma_f32_16x16x32_bf16 v[74:77], v[154:157], v[178:181], v[74:77]
	v_mfma_f32_16x16x32_bf16 v[70:73], v[146:149], v[186:189], v[70:73]
	v_mfma_f32_16x16x32_bf16 v[66:69], v[154:157], v[186:189], v[66:69]
	v_mfma_f32_16x16x32_bf16 v[94:97], v[150:153], v[166:169], v[94:97]
	v_mfma_f32_16x16x32_bf16 v[90:93], v[158:161], v[166:169], v[90:93]
	v_mfma_f32_16x16x32_bf16 v[86:89], v[150:153], v[174:177], v[86:89]
	v_mfma_f32_16x16x32_bf16 v[82:85], v[158:161], v[174:177], v[82:85]
	v_mfma_f32_16x16x32_bf16 v[78:81], v[150:153], v[182:185], v[78:81]
	v_mfma_f32_16x16x32_bf16 v[74:77], v[158:161], v[182:185], v[74:77]
	v_mfma_f32_16x16x32_bf16 v[70:73], v[150:153], v[190:193], v[70:73]
	v_mfma_f32_16x16x32_bf16 v[66:69], v[158:161], v[190:193], v[66:69]
	s_barrier
	s_add_i32 s14, s29, s93
	v_lshl_add_u64 v[212:213], s[16:17], 0, v[200:201]
	s_mov_b32 m0, s14
	ds_read_b128 v[162:165], v228 offset:16384
	ds_read_b128 v[166:169], v228 offset:17408
	ds_read_b128 v[170:173], v228 offset:18432
	ds_read_b128 v[174:177], v228 offset:19456
	ds_read_b128 v[178:181], v228 offset:20480
	ds_read_b128 v[182:185], v228 offset:21504
	ds_read_b128 v[186:189], v228 offset:22528
	ds_read_b128 v[190:193], v228 offset:23552
	global_load_lds_dwordx4 v[212:213], off
	s_add_i32 m0, s14, 0x2000
	s_add_u32 s14, s16, 0x40000
	v_lshl_add_u64 v[214:215], s[16:17], 0, v[204:205]
	s_addc_u32 s15, s17, 0
	s_add_i32 s45, s30, s93
	global_load_lds_dwordx4 v[214:215], off
	v_lshl_add_u64 v[216:217], s[14:15], 0, v[200:201]
	s_mov_b32 m0, s45
	v_lshl_add_u64 v[218:219], vcc, 0, v[202:203]
	global_load_lds_dwordx4 v[216:217], off
	v_lshl_add_u64 v[216:217], s[14:15], 0, v[204:205]
	s_add_i32 m0, s45, 0x2000
	s_nop 0
	global_load_lds_dwordx4 v[216:217], off
	v_lshl_add_u64 v[216:217], vcc, 0, v[198:199]
	s_mov_b32 m0, s94
	s_nop 0
	global_load_lds_dwordx4 v[216:217], off
	s_mov_b32 m0, s95
	s_nop 0
	global_load_lds_dwordx4 v[218:219], off
	s_waitcnt vmcnt(8)
	s_waitcnt lgkmcnt(0)
	s_barrier
; #define PG8_STAGE(bufoff, gbase, voff) do { _Pragma("unroll") for (int _i = 0; _i < 2; ++_i) \
;         __builtin_amdgcn_global_load_lds((const unsigned*)((const char*)(gbase) + (voff)[_i]), (LAS unsigned*)(lds + (bufoff) + ldsw + _i * 8192), 16, 0, 0); } while (0)
; #define PG8_LDA(dst, b, h) do { _Pragma("unroll") for (int m = 0; m < 4; ++m) _Pragma("unroll") for (int k = 0; k < 2; ++k) dst[m][k] = *(const LAS bf16x8*)(lds + PG8_SA(b, h) + aoff + m * 2048 + k * 1024); } while (0)
; #define PG8_LDB(dst, b, h) do { _Pragma("unroll") for (int n = 0; n < 2; ++n) _Pragma("unroll") for (int k = 0; k < 2; ++k) dst[n][k] = *(const LAS bf16x8*)(lds + PG8_SB(b, h) + boff + n * 2048 + k * 1024); } while (0)
; #define PG8_MMA(ai, bj, At, Bt) do { __builtin_amdgcn_s_setprio(1); _Pragma("unroll") for (int m = 0; m < 4; ++m) _Pragma("unroll") for (int n = 0; n < 2; ++n) _Pragma("unroll") for (int k = 0; k < 2; ++k) \
;         acc[ai][bj][m][n] = __builtin_amdgcn_mfma_f32_16x16x32_bf16(Bt[n][k], At[m][k], acc[ai][bj][m][n], 0, 0, 0); __builtin_amdgcn_s_setprio(0); } while (0)
; #define PG8_WAIT_V(n) asm volatile("s_waitcnt vmcnt(" #n ")" ::: "memory")
; #define PG8_WAIT_L(n) asm volatile("s_waitcnt lgkmcnt(" #n ")" ::: "memory")
; #define PG8_BAR __builtin_amdgcn_s_barrier()
; #define PG8_SCHED __builtin_amdgcn_sched_barrier(0)
; template <class Epi, int AC0, int BC0, int NT0, int AC1, int BC1, int NT1>
; __device__ __forceinline__ void gemm_phase(LAS unsigned char* lds, const Gemm g, const StaticOrder& S, const Epi& E, int tid) {
;     ...
;             PG8_WAIT_V(8); PG8_WAIT_L(0); PG8_BAR; PG8_MMA(1, 0, At, B0); PG8_MMA(1, 1, At, B1); PG8_BAR; PG8_SCHED;
;             PG8_LDB(B0, 1, 0); PG8_LDB(B1, 1, 1); PG8_SCHED; PG8_LDA(At, 1, 0); PG8_STAGE(PG8_SA(0, 1), a2 + hstepA, voffA);
;             PG8_WAIT_V(8); PG8_WAIT_L(0); PG8_BAR; PG8_MMA(0, 0, At, B0); PG8_MMA(0, 1, At, B1); PG8_BAR; PG8_SCHED;
	s_waitcnt lgkmcnt(0)
	v_mfma_f32_16x16x32_bf16 v[62:65], v[130:133], v[162:165], v[62:65]
	v_mfma_f32_16x16x32_bf16 v[58:61], v[138:141], v[162:165], v[58:61]
	v_mfma_f32_16x16x32_bf16 v[54:57], v[130:133], v[170:173], v[54:57]
	v_mfma_f32_16x16x32_bf16 v[50:53], v[138:141], v[170:173], v[50:53]
	v_mfma_f32_16x16x32_bf16 v[46:49], v[130:133], v[178:181], v[46:49]
	v_mfma_f32_16x16x32_bf16 v[42:45], v[138:141], v[178:181], v[42:45]
	v_mfma_f32_16x16x32_bf16 v[38:41], v[130:133], v[186:189], v[38:41]
	v_mfma_f32_16x16x32_bf16 v[34:37], v[138:141], v[186:189], v[34:37]
	v_mfma_f32_16x16x32_bf16 v[62:65], v[134:137], v[166:169], v[62:65]
	v_mfma_f32_16x16x32_bf16 v[58:61], v[142:145], v[166:169], v[58:61]
	v_mfma_f32_16x16x32_bf16 v[54:57], v[134:137], v[174:177], v[54:57]
	v_mfma_f32_16x16x32_bf16 v[50:53], v[142:145], v[174:177], v[50:53]
	v_mfma_f32_16x16x32_bf16 v[46:49], v[134:137], v[182:185], v[46:49]
	v_mfma_f32_16x16x32_bf16 v[42:45], v[142:145], v[182:185], v[42:45]
	v_mfma_f32_16x16x32_bf16 v[38:41], v[134:137], v[190:193], v[38:41]
	v_mfma_f32_16x16x32_bf16 v[34:37], v[142:145], v[190:193], v[34:37]
	v_mfma_f32_16x16x32_bf16 v[30:33], v[146:149], v[162:165], v[30:33]
	v_mfma_f32_16x16x32_bf16 v[26:29], v[154:157], v[162:165], v[26:29]
	v_mfma_f32_16x16x32_bf16 v[22:25], v[146:149], v[170:173], v[22:25]
	v_mfma_f32_16x16x32_bf16 v[18:21], v[154:157], v[170:173], v[18:21]
	v_mfma_f32_16x16x32_bf16 v[14:17], v[146:149], v[178:181], v[14:17]
	v_mfma_f32_16x16x32_bf16 v[10:13], v[154:157], v[178:181], v[10:13]
	v_mfma_f32_16x16x32_bf16 v[6:9], v[146:149], v[186:189], v[6:9]
	v_mfma_f32_16x16x32_bf16 v[2:5], v[154:157], v[186:189], v[2:5]
	v_mfma_f32_16x16x32_bf16 v[30:33], v[150:153], v[166:169], v[30:33]
	v_mfma_f32_16x16x32_bf16 v[26:29], v[158:161], v[166:169], v[26:29]
	v_mfma_f32_16x16x32_bf16 v[22:25], v[150:153], v[174:177], v[22:25]
	v_mfma_f32_16x16x32_bf16 v[18:21], v[158:161], v[174:177], v[18:21]
	v_mfma_f32_16x16x32_bf16 v[14:17], v[150:153], v[182:185], v[14:17]
	v_mfma_f32_16x16x32_bf16 v[10:13], v[158:161], v[182:185], v[10:13]
	v_mfma_f32_16x16x32_bf16 v[6:9], v[150:153], v[190:193], v[6:9]
	v_mfma_f32_16x16x32_bf16 v[2:5], v[158:161], v[190:193], v[2:5]
	s_barrier
	s_add_i32 s45, 0, 0x18000
	s_add_i32 s52, 0, 0x1c000
	v_add_u32_e32 v142, s45, v222
	v_add_u32_e32 v158, s52, v222
	ds_read_b128 v[130:133], v142
	ds_read_b128 v[134:137], v142 offset:1024
	ds_read_b128 v[138:141], v142 offset:2048
	ds_read_b128 v[142:145], v142 offset:3072
	ds_read_b128 v[146:149], v158
	ds_read_b128 v[150:153], v158 offset:1024
	ds_read_b128 v[154:157], v158 offset:2048
	ds_read_b128 v[158:161], v158 offset:3072
	s_add_u32 s14, vcc_lo, 0x150000
	s_addc_u32 s15, vcc_hi, 0
	s_mov_b32 m0, s24
	v_lshl_add_u64 v[220:221], s[14:15], 0, v[198:199]
	ds_read_b128 v[162:165], v228 offset:32768
	ds_read_b128 v[166:169], v228 offset:33792
	ds_read_b128 v[170:173], v228 offset:34816
	ds_read_b128 v[174:177], v228 offset:35840
	ds_read_b128 v[178:181], v228 offset:36864
	ds_read_b128 v[182:185], v228 offset:37888
	ds_read_b128 v[186:189], v228 offset:38912
	ds_read_b128 v[190:193], v228 offset:39936
	global_load_lds_dwordx4 v[220:221], off
	v_lshl_add_u64 v[220:221], s[14:15], 0, v[202:203]
	s_mov_b32 m0, s25
	s_nop 0
	global_load_lds_dwordx4 v[220:221], off
	s_waitcnt vmcnt(8)
	s_waitcnt lgkmcnt(0)
	s_barrier
	s_waitcnt lgkmcnt(0)
	v_mfma_f32_16x16x32_bf16 v[126:129], v[130:133], v[162:165], v[126:129]
	v_mfma_f32_16x16x32_bf16 v[122:125], v[138:141], v[162:165], v[122:125]
	v_mfma_f32_16x16x32_bf16 v[118:121], v[130:133], v[170:173], v[118:121]
	v_mfma_f32_16x16x32_bf16 v[114:117], v[138:141], v[170:173], v[114:117]
	v_mfma_f32_16x16x32_bf16 v[110:113], v[130:133], v[178:181], v[110:113]
	v_mfma_f32_16x16x32_bf16 v[106:109], v[138:141], v[178:181], v[106:109]
	v_mfma_f32_16x16x32_bf16 v[102:105], v[130:133], v[186:189], v[102:105]
	v_mfma_f32_16x16x32_bf16 v[98:101], v[138:141], v[186:189], v[98:101]
	v_mfma_f32_16x16x32_bf16 v[126:129], v[134:137], v[166:169], v[126:129]
	v_mfma_f32_16x16x32_bf16 v[122:125], v[142:145], v[166:169], v[122:125]
	v_mfma_f32_16x16x32_bf16 v[118:121], v[134:137], v[174:177], v[118:121]
	v_mfma_f32_16x16x32_bf16 v[114:117], v[142:145], v[174:177], v[114:117]
	v_mfma_f32_16x16x32_bf16 v[110:113], v[134:137], v[182:185], v[110:113]
	v_mfma_f32_16x16x32_bf16 v[106:109], v[142:145], v[182:185], v[106:109]
	v_mfma_f32_16x16x32_bf16 v[102:105], v[134:137], v[190:193], v[102:105]
	v_mfma_f32_16x16x32_bf16 v[98:101], v[142:145], v[190:193], v[98:101]
	v_mfma_f32_16x16x32_bf16 v[94:97], v[146:149], v[162:165], v[94:97]
	v_mfma_f32_16x16x32_bf16 v[90:93], v[154:157], v[162:165], v[90:93]
	v_mfma_f32_16x16x32_bf16 v[86:89], v[146:149], v[170:173], v[86:89]
	v_mfma_f32_16x16x32_bf16 v[82:85], v[154:157], v[170:173], v[82:85]
	v_mfma_f32_16x16x32_bf16 v[78:81], v[146:149], v[178:181], v[78:81]
	v_mfma_f32_16x16x32_bf16 v[74:77], v[154:157], v[178:181], v[74:77]
	v_mfma_f32_16x16x32_bf16 v[70:73], v[146:149], v[186:189], v[70:73]
	v_mfma_f32_16x16x32_bf16 v[66:69], v[154:157], v[186:189], v[66:69]
	v_mfma_f32_16x16x32_bf16 v[94:97], v[150:153], v[166:169], v[94:97]
	v_mfma_f32_16x16x32_bf16 v[90:93], v[158:161], v[166:169], v[90:93]
	v_mfma_f32_16x16x32_bf16 v[86:89], v[150:153], v[174:177], v[86:89]
	v_mfma_f32_16x16x32_bf16 v[82:85], v[158:161], v[174:177], v[82:85]
	v_mfma_f32_16x16x32_bf16 v[78:81], v[150:153], v[182:185], v[78:81]
	v_mfma_f32_16x16x32_bf16 v[74:77], v[158:161], v[182:185], v[74:77]
	v_mfma_f32_16x16x32_bf16 v[70:73], v[150:153], v[190:193], v[70:73]
	v_mfma_f32_16x16x32_bf16 v[66:69], v[158:161], v[190:193], v[66:69]
	s_barrier
; #define PG8_STAGE(bufoff, gbase, voff) do { _Pragma("unroll") for (int _i = 0; _i < 2; ++_i) \
;         __builtin_amdgcn_global_load_lds((const unsigned*)((const char*)(gbase) + (voff)[_i]), (LAS unsigned*)(lds + (bufoff) + ldsw + _i * 8192), 16, 0, 0); } while (0)
; #define PG8_LDA(dst, b, h) do { _Pragma("unroll") for (int m = 0; m < 4; ++m) _Pragma("unroll") for (int k = 0; k < 2; ++k) dst[m][k] = *(const LAS bf16x8*)(lds + PG8_SA(b, h) + aoff + m * 2048 + k * 1024); } while (0)
; #define PG8_MMA(ai, bj, At, Bt) do { __builtin_amdgcn_s_setprio(1); _Pragma("unroll") for (int m = 0; m < 4; ++m) _Pragma("unroll") for (int n = 0; n < 2; ++n) _Pragma("unroll") for (int k = 0; k < 2; ++k) \
;         acc[ai][bj][m][n] = __builtin_amdgcn_mfma_f32_16x16x32_bf16(Bt[n][k], At[m][k], acc[ai][bj][m][n], 0, 0, 0); __builtin_amdgcn_s_setprio(0); } while (0)
; #define PG8_WAIT_V(n) asm volatile("s_waitcnt vmcnt(" #n ")" ::: "memory")
; #define PG8_WAIT_L(n) asm volatile("s_waitcnt lgkmcnt(" #n ")" ::: "memory")
; #define PG8_BAR __builtin_amdgcn_s_barrier()
; #define PG8_SCHED __builtin_amdgcn_sched_barrier(0)
; template <class Epi, int AC0, int BC0, int NT0, int AC1, int BC1, int NT1>
; __device__ __forceinline__ void gemm_phase(LAS unsigned char* lds, const Gemm g, const StaticOrder& S, const Epi& E, int tid) {
;     ...
;             PG8_LDA(At, 1, 1); PG8_STAGE(PG8_SB(1, 0), b3, voffB); PG8_STAGE(PG8_SB(1, 1), b3 + hstepB, voffB); PG8_STAGE(PG8_SA(1, 0), a3, voffA);
;             PG8_WAIT_V(8); PG8_WAIT_L(0); PG8_BAR; PG8_MMA(1, 0, At, B0); PG8_MMA(1, 1, At, B1); PG8_BAR; PG8_SCHED;
;         }
	s_add_i32 s14, s45, s93
	v_lshl_add_u64 v[212:213], v[212:213], 0, s[4:5]
	s_mov_b32 m0, s14
	ds_read_b128 v[162:165], v228 offset:49152
	ds_read_b128 v[166:169], v228 offset:50176
	ds_read_b128 v[170:173], v228 offset:51200
	ds_read_b128 v[174:177], v228 offset:52224
	ds_read_b128 v[178:181], v228 offset:53248
	ds_read_b128 v[182:185], v228 offset:54272
	ds_read_b128 v[186:189], v228 offset:55296
	ds_read_b128 v[190:193], v228 offset:56320
	global_load_lds_dwordx4 v[212:213], off
	s_add_i32 m0, s14, 0x2000
	s_add_u32 s14, s16, 0x40080
	v_lshl_add_u64 v[212:213], v[214:215], 0, s[4:5]
	s_addc_u32 s15, s17, 0
	s_add_i32 s16, s52, s93
	global_load_lds_dwordx4 v[212:213], off
	v_lshl_add_u64 v[212:213], s[14:15], 0, v[200:201]
	s_mov_b32 m0, s16
	s_nop 0
	global_load_lds_dwordx4 v[212:213], off
	v_lshl_add_u64 v[212:213], s[14:15], 0, v[204:205]
	s_add_i32 m0, s16, 0x2000
	s_nop 0
	global_load_lds_dwordx4 v[212:213], off
	v_lshl_add_u64 v[212:213], v[216:217], 0, s[4:5]
	s_mov_b32 m0, s26
	s_nop 0
	global_load_lds_dwordx4 v[212:213], off
	v_lshl_add_u64 v[212:213], v[218:219], 0, s[4:5]
	s_mov_b32 m0, s27
	s_nop 0
	global_load_lds_dwordx4 v[212:213], off
	s_waitcnt vmcnt(8)
	s_waitcnt lgkmcnt(0)
	s_barrier
	s_waitcnt lgkmcnt(0)
	v_mfma_f32_16x16x32_bf16 v[62:65], v[130:133], v[162:165], v[62:65]
	v_mfma_f32_16x16x32_bf16 v[58:61], v[138:141], v[162:165], v[58:61]
	v_mfma_f32_16x16x32_bf16 v[54:57], v[130:133], v[170:173], v[54:57]
	v_mfma_f32_16x16x32_bf16 v[50:53], v[138:141], v[170:173], v[50:53]
	v_mfma_f32_16x16x32_bf16 v[46:49], v[130:133], v[178:181], v[46:49]
	v_mfma_f32_16x16x32_bf16 v[42:45], v[138:141], v[178:181], v[42:45]
	v_mfma_f32_16x16x32_bf16 v[38:41], v[130:133], v[186:189], v[38:41]
	v_mfma_f32_16x16x32_bf16 v[34:37], v[138:141], v[186:189], v[34:37]
	v_mfma_f32_16x16x32_bf16 v[62:65], v[134:137], v[166:169], v[62:65]
	v_mfma_f32_16x16x32_bf16 v[58:61], v[142:145], v[166:169], v[58:61]
	v_mfma_f32_16x16x32_bf16 v[54:57], v[134:137], v[174:177], v[54:57]
	v_mfma_f32_16x16x32_bf16 v[50:53], v[142:145], v[174:177], v[50:53]
	v_mfma_f32_16x16x32_bf16 v[46:49], v[134:137], v[182:185], v[46:49]
	v_mfma_f32_16x16x32_bf16 v[42:45], v[142:145], v[182:185], v[42:45]
	v_mfma_f32_16x16x32_bf16 v[38:41], v[134:137], v[190:193], v[38:41]
	v_mfma_f32_16x16x32_bf16 v[34:37], v[142:145], v[190:193], v[34:37]
	v_mfma_f32_16x16x32_bf16 v[30:33], v[146:149], v[162:165], v[30:33]
	v_mfma_f32_16x16x32_bf16 v[26:29], v[154:157], v[162:165], v[26:29]
	v_mfma_f32_16x16x32_bf16 v[22:25], v[146:149], v[170:173], v[22:25]
	v_mfma_f32_16x16x32_bf16 v[18:21], v[154:157], v[170:173], v[18:21]
	v_mfma_f32_16x16x32_bf16 v[14:17], v[146:149], v[178:181], v[14:17]
	v_mfma_f32_16x16x32_bf16 v[10:13], v[154:157], v[178:181], v[10:13]
	v_mfma_f32_16x16x32_bf16 v[6:9], v[146:149], v[186:189], v[6:9]
	v_mfma_f32_16x16x32_bf16 v[2:5], v[154:157], v[186:189], v[2:5]
	v_mfma_f32_16x16x32_bf16 v[30:33], v[150:153], v[166:169], v[30:33]
	v_mfma_f32_16x16x32_bf16 v[26:29], v[158:161], v[166:169], v[26:29]
	v_mfma_f32_16x16x32_bf16 v[22:25], v[150:153], v[174:177], v[22:25]
	v_mfma_f32_16x16x32_bf16 v[18:21], v[158:161], v[174:177], v[18:21]
	v_mfma_f32_16x16x32_bf16 v[14:17], v[150:153], v[182:185], v[14:17]
	v_mfma_f32_16x16x32_bf16 v[10:13], v[158:161], v[182:185], v[10:13]
	v_mfma_f32_16x16x32_bf16 v[6:9], v[150:153], v[190:193], v[6:9]
	v_mfma_f32_16x16x32_bf16 v[2:5], v[158:161], v[190:193], v[2:5]
	s_barrier
	s_add_i32 s42, s42, 2
	s_add_u32 s33, s33, 0x100
	s_addc_u32 s37, s37, 0
	s_cmp_gt_u32 s42, 5
	s_mov_b64 s[14:15], s[0:1]
	s_cbranch_scc0 .LBB0_725
	s_and_b64 vcc, exec, s[6:7]
	s_cbranch_vccz .LBB0_728
	s_barrier

; #define PG8_STAGE(bufoff, gbase, voff) do { _Pragma("unroll") for (int _i = 0; _i < 2; ++_i) \
;         __builtin_amdgcn_global_load_lds((const unsigned*)((const char*)(gbase) + (voff)[_i]), (LAS unsigned*)(lds + (bufoff) + ldsw + _i * 8192), 16, 0, 0); } while (0)
; #define PG8_LDA(dst, b, h) do { _Pragma("unroll") for (int m = 0; m < 4; ++m) _Pragma("unroll") for (int k = 0; k < 2; ++k) dst[m][k] = *(const LAS bf16x8*)(lds + PG8_SA(b, h) + aoff + m * 2048 + k * 1024); } while (0)
; #define PG8_LDB(dst, b, h) do { _Pragma("unroll") for (int n = 0; n < 2; ++n) _Pragma("unroll") for (int k = 0; k < 2; ++k) dst[n][k] = *(const LAS bf16x8*)(lds + PG8_SB(b, h) + boff + n * 2048 + k * 1024); } while (0)
; #define PG8_MMA(ai, bj, At, Bt) do { __builtin_amdgcn_s_setprio(1); _Pragma("unroll") for (int m = 0; m < 4; ++m) _Pragma("unroll") for (int n = 0; n < 2; ++n) _Pragma("unroll") for (int k = 0; k < 2; ++k) \
;         acc[ai][bj][m][n] = __builtin_amdgcn_mfma_f32_16x16x32_bf16(Bt[n][k], At[m][k], acc[ai][bj][m][n], 0, 0, 0); __builtin_amdgcn_s_setprio(0); } while (0)
; #define PG8_WAIT_V(n) asm volatile("s_waitcnt vmcnt(" #n ")" ::: "memory")
; #define PG8_WAIT_L(n) asm volatile("s_waitcnt lgkmcnt(" #n ")" ::: "memory")
; #define PG8_BAR __builtin_amdgcn_s_barrier()
; template <class Epi, int AC0, int BC0, int NT0, int AC1, int BC1, int NT1>
; __device__ __forceinline__ void gemm_phase(LAS unsigned char* lds, const Gemm g, const StaticOrder& S, const Epi& E, int tid) {
;     ...
;         for (int t = 0; t < nt; t += 2) {
;             const bool last = (t == nt - 2);
;             const char* a1 = cA + (size_t)(t + 1) * kstep;
;             const char* a2 = last ? nA : cA + (size_t)(t + 2) * kstep; const char* b2 = last ? nB : cB + (size_t)(t + 2) * kstep;
;             const char* a3 = a2 + kstep; const char* b3 = b2 + kstep;
;             PG8_LDB(B0, 0, 0); PG8_LDB(B1, 0, 1); PG8_SCHED; PG8_LDA(At, 0, 0); PG8_STAGE(PG8_SA(1, 1), a1 + hstepA, voffA);
;             PG8_WAIT_V(8); PG8_WAIT_L(0); PG8_BAR; PG8_MMA(0, 0, At, B0); PG8_MMA(0, 1, At, B1); PG8_BAR; PG8_SCHED;
;             PG8_LDA(At, 0, 1); PG8_STAGE(PG8_SB(0, 0), b2, voffB); PG8_STAGE(PG8_SB(0, 1), b2 + hstepB, voffB); PG8_STAGE(PG8_SA(0, 0), a2, voffA);
;             PG8_WAIT_V(8); PG8_WAIT_L(0); PG8_BAR; PG8_MMA(1, 0, At, B0); PG8_MMA(1, 1, At, B1); PG8_BAR; PG8_SCHED;
.Lpeel_P4:
	ds_read_b128 v[130:133], v218
	ds_read_b128 v[134:137], v218 offset:1024
	ds_read_b128 v[138:141], v218 offset:2048
	ds_read_b128 v[142:145], v218 offset:3072
	ds_read_b128 v[146:149], v219
	ds_read_b128 v[150:153], v219 offset:1024
	ds_read_b128 v[154:157], v219 offset:2048
	ds_read_b128 v[158:161], v219 offset:3072
	s_add_u32 s20, s18, 0xfffc0080
	s_addc_u32 s21, s19, -1
	s_cmp_eq_u32 s73, 12
	s_cselect_b32 s67, s0, s21
	s_cselect_b32 s66, s2, s20
	s_cselect_b32 s21, s3, s33
	s_cselect_b32 s20, s13, s15
	v_lshl_add_u64 v[212:213], s[18:19], 0, v[198:199]
	s_add_i32 m0, s26, 0xc000
	ds_read_b128 v[162:165], v220
	ds_read_b128 v[166:169], v220 offset:1024
	ds_read_b128 v[170:173], v220 offset:2048
	ds_read_b128 v[174:177], v220 offset:3072
	ds_read_b128 v[178:181], v220 offset:4096
	ds_read_b128 v[182:185], v220 offset:5120
	ds_read_b128 v[204:207], v220 offset:6144
	ds_read_b128 v[208:211], v220 offset:7168
	global_load_lds_dwordx4 v[212:213], off
	v_lshl_add_u64 v[212:213], s[18:19], 0, v[200:201]
	s_add_i32 m0, s26, 0xe000
	s_nop 0
	global_load_lds_dwordx4 v[212:213], off
	s_waitcnt vmcnt(56)
	s_waitcnt lgkmcnt(0)
	s_barrier
	s_waitcnt lgkmcnt(0)
	v_mfma_f32_16x16x32_bf16 v[126:129], v[130:133], v[162:165], 0
	v_mfma_f32_16x16x32_bf16 v[122:125], v[138:141], v[162:165], 0
	v_mfma_f32_16x16x32_bf16 v[110:113], v[130:133], v[170:173], 0
	v_mfma_f32_16x16x32_bf16 v[106:109], v[138:141], v[170:173], 0
	v_mfma_f32_16x16x32_bf16 v[94:97], v[130:133], v[178:181], 0
	v_mfma_f32_16x16x32_bf16 v[90:93], v[138:141], v[178:181], 0
	v_mfma_f32_16x16x32_bf16 v[78:81], v[130:133], v[204:207], 0
	v_mfma_f32_16x16x32_bf16 v[74:77], v[138:141], v[204:207], 0
	v_mfma_f32_16x16x32_bf16 v[126:129], v[134:137], v[166:169], v[126:129]
	v_mfma_f32_16x16x32_bf16 v[122:125], v[142:145], v[166:169], v[122:125]
	v_mfma_f32_16x16x32_bf16 v[110:113], v[134:137], v[174:177], v[110:113]
	v_mfma_f32_16x16x32_bf16 v[106:109], v[142:145], v[174:177], v[106:109]
	v_mfma_f32_16x16x32_bf16 v[94:97], v[134:137], v[182:185], v[94:97]
	v_mfma_f32_16x16x32_bf16 v[90:93], v[142:145], v[182:185], v[90:93]
	v_mfma_f32_16x16x32_bf16 v[78:81], v[134:137], v[208:211], v[78:81]
	v_mfma_f32_16x16x32_bf16 v[74:77], v[142:145], v[208:211], v[74:77]
	v_mfma_f32_16x16x32_bf16 v[118:121], v[146:149], v[162:165], 0
	v_mfma_f32_16x16x32_bf16 v[114:117], v[154:157], v[162:165], 0
	v_mfma_f32_16x16x32_bf16 v[102:105], v[146:149], v[170:173], 0
	v_mfma_f32_16x16x32_bf16 v[98:101], v[154:157], v[170:173], 0
	v_mfma_f32_16x16x32_bf16 v[86:89], v[146:149], v[178:181], 0
	v_mfma_f32_16x16x32_bf16 v[82:85], v[154:157], v[178:181], 0
	v_mfma_f32_16x16x32_bf16 v[70:73], v[146:149], v[204:207], 0
	v_mfma_f32_16x16x32_bf16 v[66:69], v[154:157], v[204:207], 0
	v_mfma_f32_16x16x32_bf16 v[118:121], v[150:153], v[166:169], v[118:121]
	v_mfma_f32_16x16x32_bf16 v[114:117], v[158:161], v[166:169], v[114:117]
	v_mfma_f32_16x16x32_bf16 v[102:105], v[150:153], v[174:177], v[102:105]
	v_mfma_f32_16x16x32_bf16 v[98:101], v[158:161], v[174:177], v[98:101]
	v_mfma_f32_16x16x32_bf16 v[86:89], v[150:153], v[182:185], v[86:89]
	v_mfma_f32_16x16x32_bf16 v[82:85], v[158:161], v[182:185], v[82:85]
	v_mfma_f32_16x16x32_bf16 v[70:73], v[150:153], v[208:211], v[70:73]
	v_mfma_f32_16x16x32_bf16 v[66:69], v[158:161], v[208:211], v[66:69]
	s_barrier
	s_add_i32 s75, s52, s25
	v_lshl_add_u64 v[212:213], s[20:21], 0, v[188:189]
	s_mov_b32 m0, s75
	ds_read_b128 v[162:165], v220 offset:16384
	ds_read_b128 v[166:169], v220 offset:17408
	ds_read_b128 v[170:173], v220 offset:18432
	ds_read_b128 v[174:177], v220 offset:19456
	ds_read_b128 v[178:181], v220 offset:20480
	ds_read_b128 v[182:185], v220 offset:21504
	ds_read_b128 v[204:207], v220 offset:22528
	ds_read_b128 v[208:211], v220 offset:23552
	global_load_lds_dwordx4 v[212:213], off
	s_add_i32 m0, s75, 0x2000
	s_add_u32 s76, s20, 0x40000
	v_lshl_add_u64 v[214:215], s[20:21], 0, v[192:193]
	s_addc_u32 s77, s21, 0
	s_add_i32 s75, s53, s25
	global_load_lds_dwordx4 v[214:215], off
	v_lshl_add_u64 v[222:223], s[76:77], 0, v[188:189]
	s_mov_b32 m0, s75
	v_lshl_add_u64 v[224:225], s[66:67], 0, v[190:191]
	global_load_lds_dwordx4 v[222:223], off
	v_lshl_add_u64 v[222:223], s[76:77], 0, v[192:193]
	s_add_i32 m0, s75, 0x2000
	s_nop 0
	global_load_lds_dwordx4 v[222:223], off
	v_lshl_add_u64 v[222:223], s[66:67], 0, v[186:187]
	s_mov_b32 m0, s26
	s_nop 0
	global_load_lds_dwordx4 v[222:223], off
	s_mov_b32 m0, s27
	s_nop 0
	global_load_lds_dwordx4 v[224:225], off
	s_waitcnt vmcnt(8)
	s_waitcnt lgkmcnt(0)
	s_barrier
	s_waitcnt lgkmcnt(0)
	v_mfma_f32_16x16x32_bf16 v[62:65], v[130:133], v[162:165], 0
	v_mfma_f32_16x16x32_bf16 v[58:61], v[138:141], v[162:165], 0
	v_mfma_f32_16x16x32_bf16 v[46:49], v[130:133], v[170:173], 0
	v_mfma_f32_16x16x32_bf16 v[42:45], v[138:141], v[170:173], 0
	v_mfma_f32_16x16x32_bf16 v[30:33], v[130:133], v[178:181], 0
	v_mfma_f32_16x16x32_bf16 v[26:29], v[138:141], v[178:181], 0
	v_mfma_f32_16x16x32_bf16 v[14:17], v[130:133], v[204:207], 0
	v_mfma_f32_16x16x32_bf16 v[10:13], v[138:141], v[204:207], 0
	v_mfma_f32_16x16x32_bf16 v[62:65], v[134:137], v[166:169], v[62:65]
	v_mfma_f32_16x16x32_bf16 v[58:61], v[142:145], v[166:169], v[58:61]
	v_mfma_f32_16x16x32_bf16 v[46:49], v[134:137], v[174:177], v[46:49]
	v_mfma_f32_16x16x32_bf16 v[42:45], v[142:145], v[174:177], v[42:45]
	v_mfma_f32_16x16x32_bf16 v[30:33], v[134:137], v[182:185], v[30:33]
	v_mfma_f32_16x16x32_bf16 v[26:29], v[142:145], v[182:185], v[26:29]
	v_mfma_f32_16x16x32_bf16 v[14:17], v[134:137], v[208:211], v[14:17]
	v_mfma_f32_16x16x32_bf16 v[10:13], v[142:145], v[208:211], v[10:13]
	v_mfma_f32_16x16x32_bf16 v[54:57], v[146:149], v[162:165], 0
	v_mfma_f32_16x16x32_bf16 v[50:53], v[154:157], v[162:165], 0
	v_mfma_f32_16x16x32_bf16 v[38:41], v[146:149], v[170:173], 0
	v_mfma_f32_16x16x32_bf16 v[34:37], v[154:157], v[170:173], 0
	v_mfma_f32_16x16x32_bf16 v[22:25], v[146:149], v[178:181], 0
	v_mfma_f32_16x16x32_bf16 v[18:21], v[154:157], v[178:181], 0
	v_mfma_f32_16x16x32_bf16 v[6:9], v[146:149], v[204:207], 0
	v_mfma_f32_16x16x32_bf16 v[2:5], v[154:157], v[204:207], 0
	v_mfma_f32_16x16x32_bf16 v[54:57], v[150:153], v[166:169], v[54:57]
	v_mfma_f32_16x16x32_bf16 v[50:53], v[158:161], v[166:169], v[50:53]
	v_mfma_f32_16x16x32_bf16 v[38:41], v[150:153], v[174:177], v[38:41]
	v_mfma_f32_16x16x32_bf16 v[34:37], v[158:161], v[174:177], v[34:37]
	v_mfma_f32_16x16x32_bf16 v[22:25], v[150:153], v[182:185], v[22:25]
	v_mfma_f32_16x16x32_bf16 v[18:21], v[158:161], v[182:185], v[18:21]
	v_mfma_f32_16x16x32_bf16 v[6:9], v[150:153], v[208:211], v[6:9]
	v_mfma_f32_16x16x32_bf16 v[2:5], v[158:161], v[208:211], v[2:5]
	s_barrier
	s_branch .Lmid_P4

; #define PG8_STAGE(bufoff, gbase, voff) do { _Pragma("unroll") for (int _i = 0; _i < 2; ++_i) \
;         __builtin_amdgcn_global_load_lds((const unsigned*)((const char*)(gbase) + (voff)[_i]), (LAS unsigned*)(lds + (bufoff) + ldsw + _i * 8192), 16, 0, 0); } while (0)
; #define PG8_LDA(dst, b, h) do { _Pragma("unroll") for (int m = 0; m < 4; ++m) _Pragma("unroll") for (int k = 0; k < 2; ++k) dst[m][k] = *(const LAS bf16x8*)(lds + PG8_SA(b, h) + aoff + m * 2048 + k * 1024); } while (0)
; #define PG8_LDB(dst, b, h) do { _Pragma("unroll") for (int n = 0; n < 2; ++n) _Pragma("unroll") for (int k = 0; k < 2; ++k) dst[n][k] = *(const LAS bf16x8*)(lds + PG8_SB(b, h) + boff + n * 2048 + k * 1024); } while (0)
; #define PG8_MMA(ai, bj, At, Bt) do { __builtin_amdgcn_s_setprio(1); _Pragma("unroll") for (int m = 0; m < 4; ++m) _Pragma("unroll") for (int n = 0; n < 2; ++n) _Pragma("unroll") for (int k = 0; k < 2; ++k) \
;         acc[ai][bj][m][n] = __builtin_amdgcn_mfma_f32_16x16x32_bf16(Bt[n][k], At[m][k], acc[ai][bj][m][n], 0, 0, 0); __builtin_amdgcn_s_setprio(0); } while (0)
; #define PG8_WAIT_V(n) asm volatile("s_waitcnt vmcnt(" #n ")" ::: "memory")
; #define PG8_WAIT_L(n) asm volatile("s_waitcnt lgkmcnt(" #n ")" ::: "memory")
; #define PG8_BAR __builtin_amdgcn_s_barrier()
; #define PG8_SCHED __builtin_amdgcn_sched_barrier(0)
; template <class Epi, int AC0, int BC0, int NT0, int AC1, int BC1, int NT1>
; __device__ __forceinline__ void gemm_phase(LAS unsigned char* lds, const Gemm g, const StaticOrder& S, const Epi& E, int tid) {
;     ...
;             PG8_LDB(B0, 0, 0); PG8_LDB(B1, 0, 1); PG8_SCHED; PG8_LDA(At, 0, 0); PG8_STAGE(PG8_SA(1, 1), a1 + hstepA, voffA);
;             PG8_WAIT_V(8); PG8_WAIT_L(0); PG8_BAR; PG8_MMA(0, 0, At, B0); PG8_MMA(0, 1, At, B1); PG8_BAR; PG8_SCHED;
;             PG8_LDA(At, 0, 1); PG8_STAGE(PG8_SB(0, 0), b2, voffB); PG8_STAGE(PG8_SB(0, 1), b2 + hstepB, voffB); PG8_STAGE(PG8_SA(0, 0), a2, voffA);
;             PG8_WAIT_V(8); PG8_WAIT_L(0); PG8_BAR; PG8_MMA(1, 0, At, B0); PG8_MMA(1, 1, At, B1); PG8_BAR; PG8_SCHED;
.LBB0_899:
	ds_read_b128 v[130:133], v218
	ds_read_b128 v[134:137], v218 offset:1024
	ds_read_b128 v[138:141], v218 offset:2048
	ds_read_b128 v[142:145], v218 offset:3072
	ds_read_b128 v[146:149], v219
	ds_read_b128 v[150:153], v219 offset:1024
	ds_read_b128 v[154:157], v219 offset:2048
	ds_read_b128 v[158:161], v219 offset:3072
	s_add_u32 s20, s18, 0xfffc0080
	s_addc_u32 s21, s19, -1
	s_cmp_eq_u32 s73, 12
	s_cselect_b32 s67, s0, s21
	s_cselect_b32 s66, s2, s20
	s_cselect_b32 s21, s3, s33
	s_cselect_b32 s20, s13, s15
	v_lshl_add_u64 v[212:213], s[18:19], 0, v[198:199]
	s_add_i32 m0, s26, 0xc000
	ds_read_b128 v[162:165], v220
	ds_read_b128 v[166:169], v220 offset:1024
	ds_read_b128 v[170:173], v220 offset:2048
	ds_read_b128 v[174:177], v220 offset:3072
	ds_read_b128 v[178:181], v220 offset:4096
	ds_read_b128 v[182:185], v220 offset:5120
	ds_read_b128 v[204:207], v220 offset:6144
	ds_read_b128 v[208:211], v220 offset:7168
	global_load_lds_dwordx4 v[212:213], off
	v_lshl_add_u64 v[212:213], s[18:19], 0, v[200:201]
	s_add_i32 m0, s26, 0xe000
	s_nop 0
	global_load_lds_dwordx4 v[212:213], off
	s_waitcnt vmcnt(8)
	s_waitcnt lgkmcnt(0)
	s_barrier
	s_waitcnt lgkmcnt(0)
	v_mfma_f32_16x16x32_bf16 v[126:129], v[130:133], v[162:165], v[126:129]
	v_mfma_f32_16x16x32_bf16 v[122:125], v[138:141], v[162:165], v[122:125]
	v_mfma_f32_16x16x32_bf16 v[110:113], v[130:133], v[170:173], v[110:113]
	v_mfma_f32_16x16x32_bf16 v[106:109], v[138:141], v[170:173], v[106:109]
	v_mfma_f32_16x16x32_bf16 v[94:97], v[130:133], v[178:181], v[94:97]
	v_mfma_f32_16x16x32_bf16 v[90:93], v[138:141], v[178:181], v[90:93]
	v_mfma_f32_16x16x32_bf16 v[78:81], v[130:133], v[204:207], v[78:81]
	v_mfma_f32_16x16x32_bf16 v[74:77], v[138:141], v[204:207], v[74:77]
	v_mfma_f32_16x16x32_bf16 v[126:129], v[134:137], v[166:169], v[126:129]
	v_mfma_f32_16x16x32_bf16 v[122:125], v[142:145], v[166:169], v[122:125]
	v_mfma_f32_16x16x32_bf16 v[110:113], v[134:137], v[174:177], v[110:113]
	v_mfma_f32_16x16x32_bf16 v[106:109], v[142:145], v[174:177], v[106:109]
	v_mfma_f32_16x16x32_bf16 v[94:97], v[134:137], v[182:185], v[94:97]
	v_mfma_f32_16x16x32_bf16 v[90:93], v[142:145], v[182:185], v[90:93]
	v_mfma_f32_16x16x32_bf16 v[78:81], v[134:137], v[208:211], v[78:81]
	v_mfma_f32_16x16x32_bf16 v[74:77], v[142:145], v[208:211], v[74:77]
	v_mfma_f32_16x16x32_bf16 v[118:121], v[146:149], v[162:165], v[118:121]
	v_mfma_f32_16x16x32_bf16 v[114:117], v[154:157], v[162:165], v[114:117]
	v_mfma_f32_16x16x32_bf16 v[102:105], v[146:149], v[170:173], v[102:105]
	v_mfma_f32_16x16x32_bf16 v[98:101], v[154:157], v[170:173], v[98:101]
	v_mfma_f32_16x16x32_bf16 v[86:89], v[146:149], v[178:181], v[86:89]
	v_mfma_f32_16x16x32_bf16 v[82:85], v[154:157], v[178:181], v[82:85]
	v_mfma_f32_16x16x32_bf16 v[70:73], v[146:149], v[204:207], v[70:73]
	v_mfma_f32_16x16x32_bf16 v[66:69], v[154:157], v[204:207], v[66:69]
	v_mfma_f32_16x16x32_bf16 v[118:121], v[150:153], v[166:169], v[118:121]
	v_mfma_f32_16x16x32_bf16 v[114:117], v[158:161], v[166:169], v[114:117]
	v_mfma_f32_16x16x32_bf16 v[102:105], v[150:153], v[174:177], v[102:105]
	v_mfma_f32_16x16x32_bf16 v[98:101], v[158:161], v[174:177], v[98:101]
	v_mfma_f32_16x16x32_bf16 v[86:89], v[150:153], v[182:185], v[86:89]
	v_mfma_f32_16x16x32_bf16 v[82:85], v[158:161], v[182:185], v[82:85]
	v_mfma_f32_16x16x32_bf16 v[70:73], v[150:153], v[208:211], v[70:73]
	v_mfma_f32_16x16x32_bf16 v[66:69], v[158:161], v[208:211], v[66:69]
	s_barrier
	s_add_i32 s75, s52, s25
	v_lshl_add_u64 v[212:213], s[20:21], 0, v[188:189]
	s_mov_b32 m0, s75
	ds_read_b128 v[162:165], v220 offset:16384
	ds_read_b128 v[166:169], v220 offset:17408
	ds_read_b128 v[170:173], v220 offset:18432
	ds_read_b128 v[174:177], v220 offset:19456
	ds_read_b128 v[178:181], v220 offset:20480
	ds_read_b128 v[182:185], v220 offset:21504
	ds_read_b128 v[204:207], v220 offset:22528
	ds_read_b128 v[208:211], v220 offset:23552
	global_load_lds_dwordx4 v[212:213], off
	s_add_i32 m0, s75, 0x2000
	s_add_u32 s76, s20, 0x40000
	v_lshl_add_u64 v[214:215], s[20:21], 0, v[192:193]
	s_addc_u32 s77, s21, 0
	s_add_i32 s75, s53, s25
	global_load_lds_dwordx4 v[214:215], off
	v_lshl_add_u64 v[222:223], s[76:77], 0, v[188:189]
	s_mov_b32 m0, s75
	v_lshl_add_u64 v[224:225], s[66:67], 0, v[190:191]
	global_load_lds_dwordx4 v[222:223], off
	v_lshl_add_u64 v[222:223], s[76:77], 0, v[192:193]
	s_add_i32 m0, s75, 0x2000
	s_nop 0
	global_load_lds_dwordx4 v[222:223], off
	v_lshl_add_u64 v[222:223], s[66:67], 0, v[186:187]
	s_mov_b32 m0, s26
	s_nop 0
	global_load_lds_dwordx4 v[222:223], off
	s_mov_b32 m0, s27
	s_nop 0
	global_load_lds_dwordx4 v[224:225], off
	s_waitcnt vmcnt(8)
	s_waitcnt lgkmcnt(0)
	s_barrier
	s_waitcnt lgkmcnt(0)
	v_mfma_f32_16x16x32_bf16 v[62:65], v[130:133], v[162:165], v[62:65]
	v_mfma_f32_16x16x32_bf16 v[58:61], v[138:141], v[162:165], v[58:61]
	v_mfma_f32_16x16x32_bf16 v[46:49], v[130:133], v[170:173], v[46:49]
	v_mfma_f32_16x16x32_bf16 v[42:45], v[138:141], v[170:173], v[42:45]
	v_mfma_f32_16x16x32_bf16 v[30:33], v[130:133], v[178:181], v[30:33]
	v_mfma_f32_16x16x32_bf16 v[26:29], v[138:141], v[178:181], v[26:29]
	v_mfma_f32_16x16x32_bf16 v[14:17], v[130:133], v[204:207], v[14:17]
	v_mfma_f32_16x16x32_bf16 v[10:13], v[138:141], v[204:207], v[10:13]
	v_mfma_f32_16x16x32_bf16 v[62:65], v[134:137], v[166:169], v[62:65]
	v_mfma_f32_16x16x32_bf16 v[58:61], v[142:145], v[166:169], v[58:61]
	v_mfma_f32_16x16x32_bf16 v[46:49], v[134:137], v[174:177], v[46:49]
	v_mfma_f32_16x16x32_bf16 v[42:45], v[142:145], v[174:177], v[42:45]
	v_mfma_f32_16x16x32_bf16 v[30:33], v[134:137], v[182:185], v[30:33]
	v_mfma_f32_16x16x32_bf16 v[26:29], v[142:145], v[182:185], v[26:29]
	v_mfma_f32_16x16x32_bf16 v[14:17], v[134:137], v[208:211], v[14:17]
	v_mfma_f32_16x16x32_bf16 v[10:13], v[142:145], v[208:211], v[10:13]
	v_mfma_f32_16x16x32_bf16 v[54:57], v[146:149], v[162:165], v[54:57]
	v_mfma_f32_16x16x32_bf16 v[50:53], v[154:157], v[162:165], v[50:53]
	v_mfma_f32_16x16x32_bf16 v[38:41], v[146:149], v[170:173], v[38:41]
	v_mfma_f32_16x16x32_bf16 v[34:37], v[154:157], v[170:173], v[34:37]
	v_mfma_f32_16x16x32_bf16 v[22:25], v[146:149], v[178:181], v[22:25]
	v_mfma_f32_16x16x32_bf16 v[18:21], v[154:157], v[178:181], v[18:21]
	v_mfma_f32_16x16x32_bf16 v[6:9], v[146:149], v[204:207], v[6:9]
	v_mfma_f32_16x16x32_bf16 v[2:5], v[154:157], v[204:207], v[2:5]
	v_mfma_f32_16x16x32_bf16 v[54:57], v[150:153], v[166:169], v[54:57]
	v_mfma_f32_16x16x32_bf16 v[50:53], v[158:161], v[166:169], v[50:53]
	v_mfma_f32_16x16x32_bf16 v[38:41], v[150:153], v[174:177], v[38:41]
	v_mfma_f32_16x16x32_bf16 v[34:37], v[158:161], v[174:177], v[34:37]
	v_mfma_f32_16x16x32_bf16 v[22:25], v[150:153], v[182:185], v[22:25]
	v_mfma_f32_16x16x32_bf16 v[18:21], v[158:161], v[182:185], v[18:21]
	v_mfma_f32_16x16x32_bf16 v[6:9], v[150:153], v[208:211], v[6:9]
	v_mfma_f32_16x16x32_bf16 v[2:5], v[158:161], v[208:211], v[2:5]
	s_barrier
; #define PG8_STAGE(bufoff, gbase, voff) do { _Pragma("unroll") for (int _i = 0; _i < 2; ++_i) \
;         __builtin_amdgcn_global_load_lds((const unsigned*)((const char*)(gbase) + (voff)[_i]), (LAS unsigned*)(lds + (bufoff) + ldsw + _i * 8192), 16, 0, 0); } while (0)
; #define PG8_LDA(dst, b, h) do { _Pragma("unroll") for (int m = 0; m < 4; ++m) _Pragma("unroll") for (int k = 0; k < 2; ++k) dst[m][k] = *(const LAS bf16x8*)(lds + PG8_SA(b, h) + aoff + m * 2048 + k * 1024); } while (0)
; #define PG8_LDB(dst, b, h) do { _Pragma("unroll") for (int n = 0; n < 2; ++n) _Pragma("unroll") for (int k = 0; k < 2; ++k) dst[n][k] = *(const LAS bf16x8*)(lds + PG8_SB(b, h) + boff + n * 2048 + k * 1024); } while (0)
; #define PG8_MMA(ai, bj, At, Bt) do { __builtin_amdgcn_s_setprio(1); _Pragma("unroll") for (int m = 0; m < 4; ++m) _Pragma("unroll") for (int n = 0; n < 2; ++n) _Pragma("unroll") for (int k = 0; k < 2; ++k) \
;         acc[ai][bj][m][n] = __builtin_amdgcn_mfma_f32_16x16x32_bf16(Bt[n][k], At[m][k], acc[ai][bj][m][n], 0, 0, 0); __builtin_amdgcn_s_setprio(0); } while (0)
; #define PG8_WAIT_V(n) asm volatile("s_waitcnt vmcnt(" #n ")" ::: "memory")
; #define PG8_WAIT_L(n) asm volatile("s_waitcnt lgkmcnt(" #n ")" ::: "memory")
; #define PG8_BAR __builtin_amdgcn_s_barrier()
; #define PG8_SCHED __builtin_amdgcn_sched_barrier(0)
; template <class Epi, int AC0, int BC0, int NT0, int AC1, int BC1, int NT1>
; __device__ __forceinline__ void gemm_phase(LAS unsigned char* lds, const Gemm g, const StaticOrder& S, const Epi& E, int tid) {
;     ...
;             PG8_LDB(B0, 1, 0); PG8_LDB(B1, 1, 1); PG8_SCHED; PG8_LDA(At, 1, 0); PG8_STAGE(PG8_SA(0, 1), a2 + hstepA, voffA);
;             PG8_WAIT_V(8); PG8_WAIT_L(0); PG8_BAR; PG8_MMA(0, 0, At, B0); PG8_MMA(0, 1, At, B1); PG8_BAR; PG8_SCHED;
.Lmid_P4:
	s_add_i32 s75, 0, 0x18000
	s_add_i32 s76, 0, 0x1c000
	v_add_u32_e32 v142, s75, v216
	v_add_u32_e32 v158, s76, v216
	ds_read_b128 v[130:133], v142
	ds_read_b128 v[134:137], v142 offset:1024
	ds_read_b128 v[138:141], v142 offset:2048
	ds_read_b128 v[142:145], v142 offset:3072
	ds_read_b128 v[146:149], v158
	ds_read_b128 v[150:153], v158 offset:1024
	ds_read_b128 v[154:157], v158 offset:2048
	ds_read_b128 v[158:161], v158 offset:3072
	s_add_u32 s66, s66, 0x40000
	s_addc_u32 s67, s67, 0
	s_mov_b32 m0, s28
	v_lshl_add_u64 v[226:227], s[66:67], 0, v[186:187]
	ds_read_b128 v[162:165], v220 offset:32768
	ds_read_b128 v[166:169], v220 offset:33792
	ds_read_b128 v[170:173], v220 offset:34816
	ds_read_b128 v[174:177], v220 offset:35840
	ds_read_b128 v[178:181], v220 offset:36864
	ds_read_b128 v[182:185], v220 offset:37888
	ds_read_b128 v[204:207], v220 offset:38912
	ds_read_b128 v[208:211], v220 offset:39936
	global_load_lds_dwordx4 v[226:227], off
	v_lshl_add_u64 v[226:227], s[66:67], 0, v[190:191]
	s_mov_b32 m0, s29
	s_nop 0
	global_load_lds_dwordx4 v[226:227], off
	s_waitcnt vmcnt(8)
	s_waitcnt lgkmcnt(0)
	s_barrier
	s_waitcnt lgkmcnt(0)
	v_mfma_f32_16x16x32_bf16 v[126:129], v[130:133], v[162:165], v[126:129]
	v_mfma_f32_16x16x32_bf16 v[122:125], v[138:141], v[162:165], v[122:125]
	v_mfma_f32_16x16x32_bf16 v[110:113], v[130:133], v[170:173], v[110:113]
	v_mfma_f32_16x16x32_bf16 v[106:109], v[138:141], v[170:173], v[106:109]
	v_mfma_f32_16x16x32_bf16 v[94:97], v[130:133], v[178:181], v[94:97]
	v_mfma_f32_16x16x32_bf16 v[90:93], v[138:141], v[178:181], v[90:93]
	v_mfma_f32_16x16x32_bf16 v[78:81], v[130:133], v[204:207], v[78:81]
	v_mfma_f32_16x16x32_bf16 v[74:77], v[138:141], v[204:207], v[74:77]
	v_mfma_f32_16x16x32_bf16 v[126:129], v[134:137], v[166:169], v[126:129]
	v_mfma_f32_16x16x32_bf16 v[122:125], v[142:145], v[166:169], v[122:125]
	v_mfma_f32_16x16x32_bf16 v[110:113], v[134:137], v[174:177], v[110:113]
	v_mfma_f32_16x16x32_bf16 v[106:109], v[142:145], v[174:177], v[106:109]
	v_mfma_f32_16x16x32_bf16 v[94:97], v[134:137], v[182:185], v[94:97]
	v_mfma_f32_16x16x32_bf16 v[90:93], v[142:145], v[182:185], v[90:93]
	v_mfma_f32_16x16x32_bf16 v[78:81], v[134:137], v[208:211], v[78:81]
	v_mfma_f32_16x16x32_bf16 v[74:77], v[142:145], v[208:211], v[74:77]
	v_mfma_f32_16x16x32_bf16 v[118:121], v[146:149], v[162:165], v[118:121]
	v_mfma_f32_16x16x32_bf16 v[114:117], v[154:157], v[162:165], v[114:117]
	v_mfma_f32_16x16x32_bf16 v[102:105], v[146:149], v[170:173], v[102:105]
	v_mfma_f32_16x16x32_bf16 v[98:101], v[154:157], v[170:173], v[98:101]
	v_mfma_f32_16x16x32_bf16 v[86:89], v[146:149], v[178:181], v[86:89]
	v_mfma_f32_16x16x32_bf16 v[82:85], v[154:157], v[178:181], v[82:85]
	v_mfma_f32_16x16x32_bf16 v[70:73], v[146:149], v[204:207], v[70:73]
	v_mfma_f32_16x16x32_bf16 v[66:69], v[154:157], v[204:207], v[66:69]
	v_mfma_f32_16x16x32_bf16 v[118:121], v[150:153], v[166:169], v[118:121]
	v_mfma_f32_16x16x32_bf16 v[114:117], v[158:161], v[166:169], v[114:117]
	v_mfma_f32_16x16x32_bf16 v[102:105], v[150:153], v[174:177], v[102:105]
	v_mfma_f32_16x16x32_bf16 v[98:101], v[158:161], v[174:177], v[98:101]
	v_mfma_f32_16x16x32_bf16 v[86:89], v[150:153], v[182:185], v[86:89]
	v_mfma_f32_16x16x32_bf16 v[82:85], v[158:161], v[182:185], v[82:85]
	v_mfma_f32_16x16x32_bf16 v[70:73], v[150:153], v[208:211], v[70:73]
	v_mfma_f32_16x16x32_bf16 v[66:69], v[158:161], v[208:211], v[66:69]
	s_barrier
; #define PG8_STAGE(bufoff, gbase, voff) do { _Pragma("unroll") for (int _i = 0; _i < 2; ++_i) \
;         __builtin_amdgcn_global_load_lds((const unsigned*)((const char*)(gbase) + (voff)[_i]), (LAS unsigned*)(lds + (bufoff) + ldsw + _i * 8192), 16, 0, 0); } while (0)
; #define PG8_LDA(dst, b, h) do { _Pragma("unroll") for (int m = 0; m < 4; ++m) _Pragma("unroll") for (int k = 0; k < 2; ++k) dst[m][k] = *(const LAS bf16x8*)(lds + PG8_SA(b, h) + aoff + m * 2048 + k * 1024); } while (0)
; #define PG8_MMA(ai, bj, At, Bt) do { __builtin_amdgcn_s_setprio(1); _Pragma("unroll") for (int m = 0; m < 4; ++m) _Pragma("unroll") for (int n = 0; n < 2; ++n) _Pragma("unroll") for (int k = 0; k < 2; ++k) \
;         acc[ai][bj][m][n] = __builtin_amdgcn_mfma_f32_16x16x32_bf16(Bt[n][k], At[m][k], acc[ai][bj][m][n], 0, 0, 0); __builtin_amdgcn_s_setprio(0); } while (0)
; #define PG8_WAIT_V(n) asm volatile("s_waitcnt vmcnt(" #n ")" ::: "memory")
; #define PG8_WAIT_L(n) asm volatile("s_waitcnt lgkmcnt(" #n ")" ::: "memory")
; #define PG8_BAR __builtin_amdgcn_s_barrier()
; #define PG8_SCHED __builtin_amdgcn_sched_barrier(0)
; template <class Epi, int AC0, int BC0, int NT0, int AC1, int BC1, int NT1>
; __device__ __forceinline__ void gemm_phase(LAS unsigned char* lds, const Gemm g, const StaticOrder& S, const Epi& E, int tid) {
;     ...
;             PG8_LDA(At, 1, 1); PG8_STAGE(PG8_SB(1, 0), b3, voffB); PG8_STAGE(PG8_SB(1, 1), b3 + hstepB, voffB); PG8_STAGE(PG8_SA(1, 0), a3, voffA);
;             PG8_WAIT_V(8); PG8_WAIT_L(0); PG8_BAR; PG8_MMA(1, 0, At, B0); PG8_MMA(1, 1, At, B1); PG8_BAR; PG8_SCHED;
;         }
	s_add_i32 s66, s75, s25
	v_lshl_add_u64 v[212:213], v[212:213], 0, s[6:7]
	s_mov_b32 m0, s66
	ds_read_b128 v[162:165], v220 offset:49152
	ds_read_b128 v[166:169], v220 offset:50176
	ds_read_b128 v[170:173], v220 offset:51200
	ds_read_b128 v[174:177], v220 offset:52224
	ds_read_b128 v[178:181], v220 offset:53248
	ds_read_b128 v[182:185], v220 offset:54272
	ds_read_b128 v[204:207], v220 offset:55296
	ds_read_b128 v[208:211], v220 offset:56320
	global_load_lds_dwordx4 v[212:213], off
	s_add_i32 m0, s66, 0x2000
	s_add_u32 s20, s20, 0x40080
	v_lshl_add_u64 v[212:213], v[214:215], 0, s[6:7]
	s_addc_u32 s21, s21, 0
	s_add_i32 s66, s76, s25
	global_load_lds_dwordx4 v[212:213], off
	v_lshl_add_u64 v[212:213], s[20:21], 0, v[188:189]
	s_mov_b32 m0, s66
	s_nop 0
	global_load_lds_dwordx4 v[212:213], off
	v_lshl_add_u64 v[212:213], s[20:21], 0, v[192:193]
	s_add_i32 m0, s66, 0x2000
	s_nop 0
	global_load_lds_dwordx4 v[212:213], off
	v_lshl_add_u64 v[212:213], v[222:223], 0, s[6:7]
	s_mov_b32 m0, s35
	s_nop 0
	global_load_lds_dwordx4 v[212:213], off
	v_lshl_add_u64 v[212:213], v[224:225], 0, s[6:7]
	s_mov_b32 m0, s36
	s_nop 0
	global_load_lds_dwordx4 v[212:213], off
	s_waitcnt vmcnt(8)
	s_waitcnt lgkmcnt(0)
	s_barrier
	s_waitcnt lgkmcnt(0)
	v_mfma_f32_16x16x32_bf16 v[62:65], v[130:133], v[162:165], v[62:65]
	v_mfma_f32_16x16x32_bf16 v[58:61], v[138:141], v[162:165], v[58:61]
	v_mfma_f32_16x16x32_bf16 v[46:49], v[130:133], v[170:173], v[46:49]
	v_mfma_f32_16x16x32_bf16 v[42:45], v[138:141], v[170:173], v[42:45]
	v_mfma_f32_16x16x32_bf16 v[30:33], v[130:133], v[178:181], v[30:33]
	v_mfma_f32_16x16x32_bf16 v[26:29], v[138:141], v[178:181], v[26:29]
	v_mfma_f32_16x16x32_bf16 v[14:17], v[130:133], v[204:207], v[14:17]
	v_mfma_f32_16x16x32_bf16 v[10:13], v[138:141], v[204:207], v[10:13]
	v_mfma_f32_16x16x32_bf16 v[62:65], v[134:137], v[166:169], v[62:65]
	v_mfma_f32_16x16x32_bf16 v[58:61], v[142:145], v[166:169], v[58:61]
	v_mfma_f32_16x16x32_bf16 v[46:49], v[134:137], v[174:177], v[46:49]
	v_mfma_f32_16x16x32_bf16 v[42:45], v[142:145], v[174:177], v[42:45]
	v_mfma_f32_16x16x32_bf16 v[30:33], v[134:137], v[182:185], v[30:33]
	v_mfma_f32_16x16x32_bf16 v[26:29], v[142:145], v[182:185], v[26:29]
	v_mfma_f32_16x16x32_bf16 v[14:17], v[134:137], v[208:211], v[14:17]
	v_mfma_f32_16x16x32_bf16 v[10:13], v[142:145], v[208:211], v[10:13]
	v_mfma_f32_16x16x32_bf16 v[54:57], v[146:149], v[162:165], v[54:57]
	v_mfma_f32_16x16x32_bf16 v[50:53], v[154:157], v[162:165], v[50:53]
	v_mfma_f32_16x16x32_bf16 v[38:41], v[146:149], v[170:173], v[38:41]
	v_mfma_f32_16x16x32_bf16 v[34:37], v[154:157], v[170:173], v[34:37]
	v_mfma_f32_16x16x32_bf16 v[22:25], v[146:149], v[178:181], v[22:25]
	v_mfma_f32_16x16x32_bf16 v[18:21], v[154:157], v[178:181], v[18:21]
	v_mfma_f32_16x16x32_bf16 v[6:9], v[146:149], v[204:207], v[6:9]
	v_mfma_f32_16x16x32_bf16 v[2:5], v[154:157], v[204:207], v[2:5]
	v_mfma_f32_16x16x32_bf16 v[54:57], v[150:153], v[166:169], v[54:57]
	v_mfma_f32_16x16x32_bf16 v[50:53], v[158:161], v[166:169], v[50:53]
	v_mfma_f32_16x16x32_bf16 v[38:41], v[150:153], v[174:177], v[38:41]
	v_mfma_f32_16x16x32_bf16 v[34:37], v[158:161], v[174:177], v[34:37]
	v_mfma_f32_16x16x32_bf16 v[22:25], v[150:153], v[182:185], v[22:25]
	v_mfma_f32_16x16x32_bf16 v[18:21], v[158:161], v[182:185], v[18:21]
	v_mfma_f32_16x16x32_bf16 v[6:9], v[150:153], v[208:211], v[6:9]
	v_mfma_f32_16x16x32_bf16 v[2:5], v[158:161], v[208:211], v[2:5]
	s_barrier
	s_add_i32 s73, s73, 2
	s_add_u32 s18, s18, 0x100
	s_addc_u32 s19, s19, 0
	s_add_u32 s15, s15, 0x100
	s_addc_u32 s33, s33, 0
	s_cmp_gt_u32 s73, 13
	s_cbranch_scc0 .LBB0_899
	s_and_b64 vcc, exec, s[10:11]
	s_cbranch_vccz .LBB0_902
	s_barrier

; #define PG8_STAGE(bufoff, gbase, voff) do { _Pragma("unroll") for (int _i = 0; _i < 2; ++_i) \
;         __builtin_amdgcn_global_load_lds((const unsigned*)((const char*)(gbase) + (voff)[_i]), (LAS unsigned*)(lds + (bufoff) + ldsw + _i * 8192), 16, 0, 0); } while (0)
; #define PG8_LDA(dst, b, h) do { _Pragma("unroll") for (int m = 0; m < 4; ++m) _Pragma("unroll") for (int k = 0; k < 2; ++k) dst[m][k] = *(const LAS bf16x8*)(lds + PG8_SA(b, h) + aoff + m * 2048 + k * 1024); } while (0)
; #define PG8_LDB(dst, b, h) do { _Pragma("unroll") for (int n = 0; n < 2; ++n) _Pragma("unroll") for (int k = 0; k < 2; ++k) dst[n][k] = *(const LAS bf16x8*)(lds + PG8_SB(b, h) + boff + n * 2048 + k * 1024); } while (0)
; #define PG8_MMA(ai, bj, At, Bt) do { __builtin_amdgcn_s_setprio(1); _Pragma("unroll") for (int m = 0; m < 4; ++m) _Pragma("unroll") for (int n = 0; n < 2; ++n) _Pragma("unroll") for (int k = 0; k < 2; ++k) \
;         acc[ai][bj][m][n] = __builtin_amdgcn_mfma_f32_16x16x32_bf16(Bt[n][k], At[m][k], acc[ai][bj][m][n], 0, 0, 0); __builtin_amdgcn_s_setprio(0); } while (0)
; #define PG8_WAIT_V(n) asm volatile("s_waitcnt vmcnt(" #n ")" ::: "memory")
; #define PG8_WAIT_L(n) asm volatile("s_waitcnt lgkmcnt(" #n ")" ::: "memory")
; #define PG8_BAR __builtin_amdgcn_s_barrier()
; template <class Epi, int AC0, int BC0, int NT0, int AC1, int BC1, int NT1>
; __device__ __forceinline__ void gemm_phase(LAS unsigned char* lds, const Gemm g, const StaticOrder& S, const Epi& E, int tid) {
;     ...
;         for (int t = 0; t < nt; t += 2) {
;             const bool last = (t == nt - 2);
;             const char* a1 = cA + (size_t)(t + 1) * kstep;
;             const char* a2 = last ? nA : cA + (size_t)(t + 2) * kstep; const char* b2 = last ? nB : cB + (size_t)(t + 2) * kstep;
;             const char* a3 = a2 + kstep; const char* b3 = b2 + kstep;
;             PG8_LDB(B0, 0, 0); PG8_LDB(B1, 0, 1); PG8_SCHED; PG8_LDA(At, 0, 0); PG8_STAGE(PG8_SA(1, 1), a1 + hstepA, voffA);
;             PG8_WAIT_V(8); PG8_WAIT_L(0); PG8_BAR; PG8_MMA(0, 0, At, B0); PG8_MMA(0, 1, At, B1); PG8_BAR; PG8_SCHED;
;             PG8_LDA(At, 0, 1); PG8_STAGE(PG8_SB(0, 0), b2, voffB); PG8_STAGE(PG8_SB(0, 1), b2 + hstepB, voffB); PG8_STAGE(PG8_SA(0, 0), a2, voffA);
;             PG8_WAIT_V(8); PG8_WAIT_L(0); PG8_BAR; PG8_MMA(1, 0, At, B0); PG8_MMA(1, 1, At, B1); PG8_BAR; PG8_SCHED;
.Lpeel_P5:
	ds_read_b128 v[128:131], v231
	ds_read_b128 v[132:135], v231 offset:1024
	ds_read_b128 v[136:139], v231 offset:2048
	ds_read_b128 v[140:143], v231 offset:3072
	ds_read_b128 v[144:147], v232
	ds_read_b128 v[148:151], v232 offset:1024
	ds_read_b128 v[152:155], v232 offset:2048
	ds_read_b128 v[156:159], v232 offset:3072
	s_add_u32 s20, s18, 0x100
	s_addc_u32 s21, s19, 0
	s_cmp_eq_u32 s33, s50
	s_cselect_b32 s25, s5, s21
	s_cselect_b32 s24, s4, s20
	s_cselect_b32 s23, s15, s47
	s_cselect_b32 s22, s14, s46
	v_lshl_add_u64 v[206:207], s[18:19], 0, v[200:201]
	s_add_i32 m0, s28, 0xc000
	ds_read_b128 v[160:163], v233
	ds_read_b128 v[164:167], v233 offset:1024
	ds_read_b128 v[168:171], v233 offset:2048
	ds_read_b128 v[172:175], v233 offset:3072
	ds_read_b128 v[176:179], v233 offset:4096
	ds_read_b128 v[180:183], v233 offset:5120
	ds_read_b128 v[184:187], v233 offset:6144
	ds_read_b128 v[188:191], v233 offset:7168
	global_load_lds_dwordx4 v[206:207], off
	v_lshl_add_u64 v[206:207], s[18:19], 0, v[202:203]
	s_add_i32 m0, s28, 0xe000
	s_nop 0
	global_load_lds_dwordx4 v[206:207], off
	s_waitcnt vmcnt(24)
	s_waitcnt lgkmcnt(0)
	s_barrier
	s_waitcnt lgkmcnt(0)
	v_mfma_f32_16x16x32_bf16 v[124:127], v[128:131], v[160:163], 0
	v_mfma_f32_16x16x32_bf16 v[120:123], v[136:139], v[160:163], 0
	v_mfma_f32_16x16x32_bf16 v[116:119], v[128:131], v[168:171], 0
	v_mfma_f32_16x16x32_bf16 v[112:115], v[136:139], v[168:171], 0
	v_mfma_f32_16x16x32_bf16 v[100:103], v[128:131], v[176:179], 0
	v_mfma_f32_16x16x32_bf16 v[96:99], v[136:139], v[176:179], 0
	v_mfma_f32_16x16x32_bf16 v[84:87], v[128:131], v[184:187], 0
	v_mfma_f32_16x16x32_bf16 v[80:83], v[136:139], v[184:187], 0
	v_mfma_f32_16x16x32_bf16 v[124:127], v[132:135], v[164:167], v[124:127]
	v_mfma_f32_16x16x32_bf16 v[120:123], v[140:143], v[164:167], v[120:123]
	v_mfma_f32_16x16x32_bf16 v[116:119], v[132:135], v[172:175], v[116:119]
	v_mfma_f32_16x16x32_bf16 v[112:115], v[140:143], v[172:175], v[112:115]
	v_mfma_f32_16x16x32_bf16 v[100:103], v[132:135], v[180:183], v[100:103]
	v_mfma_f32_16x16x32_bf16 v[96:99], v[140:143], v[180:183], v[96:99]
	v_mfma_f32_16x16x32_bf16 v[84:87], v[132:135], v[188:191], v[84:87]
	v_mfma_f32_16x16x32_bf16 v[80:83], v[140:143], v[188:191], v[80:83]
	v_mfma_f32_16x16x32_bf16 v[108:111], v[144:147], v[160:163], 0
	v_mfma_f32_16x16x32_bf16 v[104:107], v[152:155], v[160:163], 0
	v_mfma_f32_16x16x32_bf16 v[92:95], v[144:147], v[168:171], 0
	v_mfma_f32_16x16x32_bf16 v[88:91], v[152:155], v[168:171], 0
	v_mfma_f32_16x16x32_bf16 v[76:79], v[144:147], v[176:179], 0
	v_mfma_f32_16x16x32_bf16 v[72:75], v[152:155], v[176:179], 0
	v_mfma_f32_16x16x32_bf16 v[68:71], v[144:147], v[184:187], 0
	v_mfma_f32_16x16x32_bf16 v[64:67], v[152:155], v[184:187], 0
	v_mfma_f32_16x16x32_bf16 v[108:111], v[148:151], v[164:167], v[108:111]
	v_mfma_f32_16x16x32_bf16 v[104:107], v[156:159], v[164:167], v[104:107]
	v_mfma_f32_16x16x32_bf16 v[92:95], v[148:151], v[172:175], v[92:95]
	v_mfma_f32_16x16x32_bf16 v[88:91], v[156:159], v[172:175], v[88:91]
	v_mfma_f32_16x16x32_bf16 v[76:79], v[148:151], v[180:183], v[76:79]
	v_mfma_f32_16x16x32_bf16 v[72:75], v[156:159], v[180:183], v[72:75]
	v_mfma_f32_16x16x32_bf16 v[68:71], v[148:151], v[188:191], v[68:71]
	v_mfma_f32_16x16x32_bf16 v[64:67], v[156:159], v[188:191], v[64:67]
	s_barrier
	s_add_i32 s18, s37, s27
	v_lshl_add_u64 v[206:207], s[22:23], 0, v[194:195]
	s_mov_b32 m0, s18
	ds_read_b128 v[160:163], v233 offset:16384
	ds_read_b128 v[164:167], v233 offset:17408
	ds_read_b128 v[168:171], v233 offset:18432
	ds_read_b128 v[172:175], v233 offset:19456
	ds_read_b128 v[176:179], v233 offset:20480
	ds_read_b128 v[180:183], v233 offset:21504
	ds_read_b128 v[184:187], v233 offset:22528
	ds_read_b128 v[188:191], v233 offset:23552
	global_load_lds_dwordx4 v[206:207], off
	s_add_i32 m0, s18, 0x2000
	s_add_u32 s18, s22, 0x50000
	v_lshl_add_u64 v[208:209], s[22:23], 0, v[198:199]
	s_addc_u32 s19, s23, 0
	s_add_i32 s51, s38, s27
	global_load_lds_dwordx4 v[208:209], off
	v_lshl_add_u64 v[210:211], s[18:19], 0, v[194:195]
	s_mov_b32 m0, s51
	v_lshl_add_u64 v[212:213], s[24:25], 0, v[196:197]
	global_load_lds_dwordx4 v[210:211], off
	v_lshl_add_u64 v[210:211], s[18:19], 0, v[198:199]
	s_add_i32 m0, s51, 0x2000
	s_nop 0
	global_load_lds_dwordx4 v[210:211], off
	v_lshl_add_u64 v[210:211], s[24:25], 0, v[192:193]
	s_mov_b32 m0, s28
	s_nop 0
	global_load_lds_dwordx4 v[210:211], off
	s_mov_b32 m0, s29
	s_nop 0
	global_load_lds_dwordx4 v[212:213], off
	s_waitcnt vmcnt(8)
	s_waitcnt lgkmcnt(0)
	s_barrier
	s_waitcnt lgkmcnt(0)
	v_mfma_f32_16x16x32_bf16 v[60:63], v[128:131], v[160:163], 0
	v_mfma_f32_16x16x32_bf16 v[56:59], v[136:139], v[160:163], 0
	v_mfma_f32_16x16x32_bf16 v[52:55], v[128:131], v[168:171], 0
	v_mfma_f32_16x16x32_bf16 v[48:51], v[136:139], v[168:171], 0
	v_mfma_f32_16x16x32_bf16 v[36:39], v[128:131], v[176:179], 0
	v_mfma_f32_16x16x32_bf16 v[32:35], v[136:139], v[176:179], 0
	v_mfma_f32_16x16x32_bf16 v[20:23], v[128:131], v[184:187], 0
	v_mfma_f32_16x16x32_bf16 v[16:19], v[136:139], v[184:187], 0
	v_mfma_f32_16x16x32_bf16 v[60:63], v[132:135], v[164:167], v[60:63]
	v_mfma_f32_16x16x32_bf16 v[56:59], v[140:143], v[164:167], v[56:59]
	v_mfma_f32_16x16x32_bf16 v[52:55], v[132:135], v[172:175], v[52:55]
	v_mfma_f32_16x16x32_bf16 v[48:51], v[140:143], v[172:175], v[48:51]
	v_mfma_f32_16x16x32_bf16 v[36:39], v[132:135], v[180:183], v[36:39]
	v_mfma_f32_16x16x32_bf16 v[32:35], v[140:143], v[180:183], v[32:35]
	v_mfma_f32_16x16x32_bf16 v[20:23], v[132:135], v[188:191], v[20:23]
	v_mfma_f32_16x16x32_bf16 v[16:19], v[140:143], v[188:191], v[16:19]
	v_mfma_f32_16x16x32_bf16 v[44:47], v[144:147], v[160:163], 0
	v_mfma_f32_16x16x32_bf16 v[40:43], v[152:155], v[160:163], 0
	v_mfma_f32_16x16x32_bf16 v[28:31], v[144:147], v[168:171], 0
	v_mfma_f32_16x16x32_bf16 v[24:27], v[152:155], v[168:171], 0
	v_mfma_f32_16x16x32_bf16 v[12:15], v[144:147], v[176:179], 0
	v_mfma_f32_16x16x32_bf16 v[8:11], v[152:155], v[176:179], 0
	v_mfma_f32_16x16x32_bf16 v[4:7], v[144:147], v[184:187], 0
	v_mfma_f32_16x16x32_bf16 v[0:3], v[152:155], v[184:187], 0
	v_mfma_f32_16x16x32_bf16 v[44:47], v[148:151], v[164:167], v[44:47]
	v_mfma_f32_16x16x32_bf16 v[40:43], v[156:159], v[164:167], v[40:43]
	v_mfma_f32_16x16x32_bf16 v[28:31], v[148:151], v[172:175], v[28:31]
	v_mfma_f32_16x16x32_bf16 v[24:27], v[156:159], v[172:175], v[24:27]
	v_mfma_f32_16x16x32_bf16 v[12:15], v[148:151], v[180:183], v[12:15]
	v_mfma_f32_16x16x32_bf16 v[8:11], v[156:159], v[180:183], v[8:11]
	v_mfma_f32_16x16x32_bf16 v[4:7], v[148:151], v[188:191], v[4:7]
	v_mfma_f32_16x16x32_bf16 v[0:3], v[156:159], v[188:191], v[0:3]
	s_barrier
	s_branch .Lmid_P5

; #define PG8_STAGE(bufoff, gbase, voff) do { _Pragma("unroll") for (int _i = 0; _i < 2; ++_i) \
;         __builtin_amdgcn_global_load_lds((const unsigned*)((const char*)(gbase) + (voff)[_i]), (LAS unsigned*)(lds + (bufoff) + ldsw + _i * 8192), 16, 0, 0); } while (0)
; #define PG8_LDA(dst, b, h) do { _Pragma("unroll") for (int m = 0; m < 4; ++m) _Pragma("unroll") for (int k = 0; k < 2; ++k) dst[m][k] = *(const LAS bf16x8*)(lds + PG8_SA(b, h) + aoff + m * 2048 + k * 1024); } while (0)
; #define PG8_LDB(dst, b, h) do { _Pragma("unroll") for (int n = 0; n < 2; ++n) _Pragma("unroll") for (int k = 0; k < 2; ++k) dst[n][k] = *(const LAS bf16x8*)(lds + PG8_SB(b, h) + boff + n * 2048 + k * 1024); } while (0)
; #define PG8_MMA(ai, bj, At, Bt) do { __builtin_amdgcn_s_setprio(1); _Pragma("unroll") for (int m = 0; m < 4; ++m) _Pragma("unroll") for (int n = 0; n < 2; ++n) _Pragma("unroll") for (int k = 0; k < 2; ++k) \
;         acc[ai][bj][m][n] = __builtin_amdgcn_mfma_f32_16x16x32_bf16(Bt[n][k], At[m][k], acc[ai][bj][m][n], 0, 0, 0); __builtin_amdgcn_s_setprio(0); } while (0)
; #define PG8_WAIT_V(n) asm volatile("s_waitcnt vmcnt(" #n ")" ::: "memory")
; #define PG8_WAIT_L(n) asm volatile("s_waitcnt lgkmcnt(" #n ")" ::: "memory")
; #define PG8_BAR __builtin_amdgcn_s_barrier()
; #define PG8_SCHED __builtin_amdgcn_sched_barrier(0)
; template <class Epi, int AC0, int BC0, int NT0, int AC1, int BC1, int NT1>
; __device__ __forceinline__ void gemm_phase(LAS unsigned char* lds, const Gemm g, const StaticOrder& S, const Epi& E, int tid) {
;     ...
;             PG8_LDB(B0, 0, 0); PG8_LDB(B1, 0, 1); PG8_SCHED; PG8_LDA(At, 0, 0); PG8_STAGE(PG8_SA(1, 1), a1 + hstepA, voffA);
;             PG8_WAIT_V(8); PG8_WAIT_L(0); PG8_BAR; PG8_MMA(0, 0, At, B0); PG8_MMA(0, 1, At, B1); PG8_BAR; PG8_SCHED;
;             PG8_LDA(At, 0, 1); PG8_STAGE(PG8_SB(0, 0), b2, voffB); PG8_STAGE(PG8_SB(0, 1), b2 + hstepB, voffB); PG8_STAGE(PG8_SA(0, 0), a2, voffA);
;             PG8_WAIT_V(8); PG8_WAIT_L(0); PG8_BAR; PG8_MMA(1, 0, At, B0); PG8_MMA(1, 1, At, B1); PG8_BAR; PG8_SCHED;
.LBB0_992:
	ds_read_b128 v[128:131], v231
	ds_read_b128 v[132:135], v231 offset:1024
	ds_read_b128 v[136:139], v231 offset:2048
	ds_read_b128 v[140:143], v231 offset:3072
	ds_read_b128 v[144:147], v232
	ds_read_b128 v[148:151], v232 offset:1024
	ds_read_b128 v[152:155], v232 offset:2048
	ds_read_b128 v[156:159], v232 offset:3072
	s_add_u32 s20, s18, 0x100
	s_addc_u32 s21, s19, 0
	s_cmp_eq_u32 s33, s50
	s_cselect_b32 s25, s5, s21
	s_cselect_b32 s24, s4, s20
	s_cselect_b32 s23, s15, s47
	s_cselect_b32 s22, s14, s46
	v_lshl_add_u64 v[206:207], s[18:19], 0, v[200:201]
	s_add_i32 m0, s28, 0xc000
	ds_read_b128 v[160:163], v233
	ds_read_b128 v[164:167], v233 offset:1024
	ds_read_b128 v[168:171], v233 offset:2048
	ds_read_b128 v[172:175], v233 offset:3072
	ds_read_b128 v[176:179], v233 offset:4096
	ds_read_b128 v[180:183], v233 offset:5120
	ds_read_b128 v[184:187], v233 offset:6144
	ds_read_b128 v[188:191], v233 offset:7168
	global_load_lds_dwordx4 v[206:207], off
	v_lshl_add_u64 v[206:207], s[18:19], 0, v[202:203]
	s_add_i32 m0, s28, 0xe000
	s_nop 0
	global_load_lds_dwordx4 v[206:207], off
	s_waitcnt vmcnt(8)
	s_waitcnt lgkmcnt(0)
	s_barrier
	s_waitcnt lgkmcnt(0)
	v_mfma_f32_16x16x32_bf16 v[124:127], v[128:131], v[160:163], v[124:127]
	v_mfma_f32_16x16x32_bf16 v[120:123], v[136:139], v[160:163], v[120:123]
	v_mfma_f32_16x16x32_bf16 v[116:119], v[128:131], v[168:171], v[116:119]
	v_mfma_f32_16x16x32_bf16 v[112:115], v[136:139], v[168:171], v[112:115]
	v_mfma_f32_16x16x32_bf16 v[100:103], v[128:131], v[176:179], v[100:103]
	v_mfma_f32_16x16x32_bf16 v[96:99], v[136:139], v[176:179], v[96:99]
	v_mfma_f32_16x16x32_bf16 v[84:87], v[128:131], v[184:187], v[84:87]
	v_mfma_f32_16x16x32_bf16 v[80:83], v[136:139], v[184:187], v[80:83]
	v_mfma_f32_16x16x32_bf16 v[124:127], v[132:135], v[164:167], v[124:127]
	v_mfma_f32_16x16x32_bf16 v[120:123], v[140:143], v[164:167], v[120:123]
	v_mfma_f32_16x16x32_bf16 v[116:119], v[132:135], v[172:175], v[116:119]
	v_mfma_f32_16x16x32_bf16 v[112:115], v[140:143], v[172:175], v[112:115]
	v_mfma_f32_16x16x32_bf16 v[100:103], v[132:135], v[180:183], v[100:103]
	v_mfma_f32_16x16x32_bf16 v[96:99], v[140:143], v[180:183], v[96:99]
	v_mfma_f32_16x16x32_bf16 v[84:87], v[132:135], v[188:191], v[84:87]
	v_mfma_f32_16x16x32_bf16 v[80:83], v[140:143], v[188:191], v[80:83]
	v_mfma_f32_16x16x32_bf16 v[108:111], v[144:147], v[160:163], v[108:111]
	v_mfma_f32_16x16x32_bf16 v[104:107], v[152:155], v[160:163], v[104:107]
	v_mfma_f32_16x16x32_bf16 v[92:95], v[144:147], v[168:171], v[92:95]
	v_mfma_f32_16x16x32_bf16 v[88:91], v[152:155], v[168:171], v[88:91]
	v_mfma_f32_16x16x32_bf16 v[76:79], v[144:147], v[176:179], v[76:79]
	v_mfma_f32_16x16x32_bf16 v[72:75], v[152:155], v[176:179], v[72:75]
	v_mfma_f32_16x16x32_bf16 v[68:71], v[144:147], v[184:187], v[68:71]
	v_mfma_f32_16x16x32_bf16 v[64:67], v[152:155], v[184:187], v[64:67]
	v_mfma_f32_16x16x32_bf16 v[108:111], v[148:151], v[164:167], v[108:111]
	v_mfma_f32_16x16x32_bf16 v[104:107], v[156:159], v[164:167], v[104:107]
	v_mfma_f32_16x16x32_bf16 v[92:95], v[148:151], v[172:175], v[92:95]
	v_mfma_f32_16x16x32_bf16 v[88:91], v[156:159], v[172:175], v[88:91]
	v_mfma_f32_16x16x32_bf16 v[76:79], v[148:151], v[180:183], v[76:79]
	v_mfma_f32_16x16x32_bf16 v[72:75], v[156:159], v[180:183], v[72:75]
	v_mfma_f32_16x16x32_bf16 v[68:71], v[148:151], v[188:191], v[68:71]
	v_mfma_f32_16x16x32_bf16 v[64:67], v[156:159], v[188:191], v[64:67]
	s_barrier
	s_add_i32 s18, s37, s27
	v_lshl_add_u64 v[206:207], s[22:23], 0, v[194:195]
	s_mov_b32 m0, s18
	ds_read_b128 v[160:163], v233 offset:16384
	ds_read_b128 v[164:167], v233 offset:17408
	ds_read_b128 v[168:171], v233 offset:18432
	ds_read_b128 v[172:175], v233 offset:19456
	ds_read_b128 v[176:179], v233 offset:20480
	ds_read_b128 v[180:183], v233 offset:21504
	ds_read_b128 v[184:187], v233 offset:22528
	ds_read_b128 v[188:191], v233 offset:23552
	global_load_lds_dwordx4 v[206:207], off
	s_add_i32 m0, s18, 0x2000
	s_add_u32 s18, s22, 0x50000
	v_lshl_add_u64 v[208:209], s[22:23], 0, v[198:199]
	s_addc_u32 s19, s23, 0
	s_add_i32 s51, s38, s27
	global_load_lds_dwordx4 v[208:209], off
	v_lshl_add_u64 v[210:211], s[18:19], 0, v[194:195]
	s_mov_b32 m0, s51
	v_lshl_add_u64 v[212:213], s[24:25], 0, v[196:197]
	global_load_lds_dwordx4 v[210:211], off
	v_lshl_add_u64 v[210:211], s[18:19], 0, v[198:199]
	s_add_i32 m0, s51, 0x2000
	s_nop 0
	global_load_lds_dwordx4 v[210:211], off
	v_lshl_add_u64 v[210:211], s[24:25], 0, v[192:193]
	s_mov_b32 m0, s28
	s_nop 0
	global_load_lds_dwordx4 v[210:211], off
	s_mov_b32 m0, s29
	s_nop 0
	global_load_lds_dwordx4 v[212:213], off
	s_waitcnt vmcnt(8)
	s_waitcnt lgkmcnt(0)
	s_barrier
	s_waitcnt lgkmcnt(0)
	v_mfma_f32_16x16x32_bf16 v[60:63], v[128:131], v[160:163], v[60:63]
	v_mfma_f32_16x16x32_bf16 v[56:59], v[136:139], v[160:163], v[56:59]
	v_mfma_f32_16x16x32_bf16 v[52:55], v[128:131], v[168:171], v[52:55]
	v_mfma_f32_16x16x32_bf16 v[48:51], v[136:139], v[168:171], v[48:51]
	v_mfma_f32_16x16x32_bf16 v[36:39], v[128:131], v[176:179], v[36:39]
	v_mfma_f32_16x16x32_bf16 v[32:35], v[136:139], v[176:179], v[32:35]
	v_mfma_f32_16x16x32_bf16 v[20:23], v[128:131], v[184:187], v[20:23]
	v_mfma_f32_16x16x32_bf16 v[16:19], v[136:139], v[184:187], v[16:19]
	v_mfma_f32_16x16x32_bf16 v[60:63], v[132:135], v[164:167], v[60:63]
	v_mfma_f32_16x16x32_bf16 v[56:59], v[140:143], v[164:167], v[56:59]
	v_mfma_f32_16x16x32_bf16 v[52:55], v[132:135], v[172:175], v[52:55]
	v_mfma_f32_16x16x32_bf16 v[48:51], v[140:143], v[172:175], v[48:51]
	v_mfma_f32_16x16x32_bf16 v[36:39], v[132:135], v[180:183], v[36:39]
	v_mfma_f32_16x16x32_bf16 v[32:35], v[140:143], v[180:183], v[32:35]
	v_mfma_f32_16x16x32_bf16 v[20:23], v[132:135], v[188:191], v[20:23]
	v_mfma_f32_16x16x32_bf16 v[16:19], v[140:143], v[188:191], v[16:19]
	v_mfma_f32_16x16x32_bf16 v[44:47], v[144:147], v[160:163], v[44:47]
	v_mfma_f32_16x16x32_bf16 v[40:43], v[152:155], v[160:163], v[40:43]
	v_mfma_f32_16x16x32_bf16 v[28:31], v[144:147], v[168:171], v[28:31]
	v_mfma_f32_16x16x32_bf16 v[24:27], v[152:155], v[168:171], v[24:27]
	v_mfma_f32_16x16x32_bf16 v[12:15], v[144:147], v[176:179], v[12:15]
	v_mfma_f32_16x16x32_bf16 v[8:11], v[152:155], v[176:179], v[8:11]
	v_mfma_f32_16x16x32_bf16 v[4:7], v[144:147], v[184:187], v[4:7]
	v_mfma_f32_16x16x32_bf16 v[0:3], v[152:155], v[184:187], v[0:3]
	v_mfma_f32_16x16x32_bf16 v[44:47], v[148:151], v[164:167], v[44:47]
	v_mfma_f32_16x16x32_bf16 v[40:43], v[156:159], v[164:167], v[40:43]
	v_mfma_f32_16x16x32_bf16 v[28:31], v[148:151], v[172:175], v[28:31]
	v_mfma_f32_16x16x32_bf16 v[24:27], v[156:159], v[172:175], v[24:27]
	v_mfma_f32_16x16x32_bf16 v[12:15], v[148:151], v[180:183], v[12:15]
	v_mfma_f32_16x16x32_bf16 v[8:11], v[156:159], v[180:183], v[8:11]
	v_mfma_f32_16x16x32_bf16 v[4:7], v[148:151], v[188:191], v[4:7]
	v_mfma_f32_16x16x32_bf16 v[0:3], v[156:159], v[188:191], v[0:3]
	s_barrier
; #define PG8_STAGE(bufoff, gbase, voff) do { _Pragma("unroll") for (int _i = 0; _i < 2; ++_i) \
;         __builtin_amdgcn_global_load_lds((const unsigned*)((const char*)(gbase) + (voff)[_i]), (LAS unsigned*)(lds + (bufoff) + ldsw + _i * 8192), 16, 0, 0); } while (0)
; #define PG8_LDA(dst, b, h) do { _Pragma("unroll") for (int m = 0; m < 4; ++m) _Pragma("unroll") for (int k = 0; k < 2; ++k) dst[m][k] = *(const LAS bf16x8*)(lds + PG8_SA(b, h) + aoff + m * 2048 + k * 1024); } while (0)
; #define PG8_LDB(dst, b, h) do { _Pragma("unroll") for (int n = 0; n < 2; ++n) _Pragma("unroll") for (int k = 0; k < 2; ++k) dst[n][k] = *(const LAS bf16x8*)(lds + PG8_SB(b, h) + boff + n * 2048 + k * 1024); } while (0)
; #define PG8_MMA(ai, bj, At, Bt) do { __builtin_amdgcn_s_setprio(1); _Pragma("unroll") for (int m = 0; m < 4; ++m) _Pragma("unroll") for (int n = 0; n < 2; ++n) _Pragma("unroll") for (int k = 0; k < 2; ++k) \
;         acc[ai][bj][m][n] = __builtin_amdgcn_mfma_f32_16x16x32_bf16(Bt[n][k], At[m][k], acc[ai][bj][m][n], 0, 0, 0); __builtin_amdgcn_s_setprio(0); } while (0)
; #define PG8_WAIT_V(n) asm volatile("s_waitcnt vmcnt(" #n ")" ::: "memory")
; #define PG8_WAIT_L(n) asm volatile("s_waitcnt lgkmcnt(" #n ")" ::: "memory")
; #define PG8_BAR __builtin_amdgcn_s_barrier()
; #define PG8_SCHED __builtin_amdgcn_sched_barrier(0)
; template <class Epi, int AC0, int BC0, int NT0, int AC1, int BC1, int NT1>
; __device__ __forceinline__ void gemm_phase(LAS unsigned char* lds, const Gemm g, const StaticOrder& S, const Epi& E, int tid) {
;     ...
;             PG8_LDB(B0, 1, 0); PG8_LDB(B1, 1, 1); PG8_SCHED; PG8_LDA(At, 1, 0); PG8_STAGE(PG8_SA(0, 1), a2 + hstepA, voffA);
;             PG8_WAIT_V(8); PG8_WAIT_L(0); PG8_BAR; PG8_MMA(0, 0, At, B0); PG8_MMA(0, 1, At, B1); PG8_BAR; PG8_SCHED;
.Lmid_P5:
	s_add_i32 s51, 0, 0x18000
	s_add_i32 s52, 0, 0x1c000
	v_add_u32_e32 v140, s51, v221
	v_add_u32_e32 v156, s52, v221
	ds_read_b128 v[128:131], v140
	ds_read_b128 v[132:135], v140 offset:1024
	ds_read_b128 v[136:139], v140 offset:2048
	ds_read_b128 v[140:143], v140 offset:3072
	ds_read_b128 v[144:147], v156
	ds_read_b128 v[148:151], v156 offset:1024
	ds_read_b128 v[152:155], v156 offset:2048
	ds_read_b128 v[156:159], v156 offset:3072
	s_add_u32 s18, s24, 0x50000
	s_addc_u32 s19, s25, 0
	s_mov_b32 m0, s30
	v_lshl_add_u64 v[214:215], s[18:19], 0, v[192:193]
	ds_read_b128 v[160:163], v233 offset:32768
	ds_read_b128 v[164:167], v233 offset:33792
	ds_read_b128 v[168:171], v233 offset:34816
	ds_read_b128 v[172:175], v233 offset:35840
	ds_read_b128 v[176:179], v233 offset:36864
	ds_read_b128 v[180:183], v233 offset:37888
	ds_read_b128 v[184:187], v233 offset:38912
	ds_read_b128 v[188:191], v233 offset:39936
	global_load_lds_dwordx4 v[214:215], off
	v_lshl_add_u64 v[214:215], s[18:19], 0, v[196:197]
	s_mov_b32 m0, s31
	s_nop 0
	global_load_lds_dwordx4 v[214:215], off
	s_waitcnt vmcnt(8)
	s_waitcnt lgkmcnt(0)
	s_barrier
	s_waitcnt lgkmcnt(0)
	v_mfma_f32_16x16x32_bf16 v[124:127], v[128:131], v[160:163], v[124:127]
	v_mfma_f32_16x16x32_bf16 v[120:123], v[136:139], v[160:163], v[120:123]
	v_mfma_f32_16x16x32_bf16 v[116:119], v[128:131], v[168:171], v[116:119]
	v_mfma_f32_16x16x32_bf16 v[112:115], v[136:139], v[168:171], v[112:115]
	v_mfma_f32_16x16x32_bf16 v[100:103], v[128:131], v[176:179], v[100:103]
	v_mfma_f32_16x16x32_bf16 v[96:99], v[136:139], v[176:179], v[96:99]
	v_mfma_f32_16x16x32_bf16 v[84:87], v[128:131], v[184:187], v[84:87]
	v_mfma_f32_16x16x32_bf16 v[80:83], v[136:139], v[184:187], v[80:83]
	v_mfma_f32_16x16x32_bf16 v[124:127], v[132:135], v[164:167], v[124:127]
	v_mfma_f32_16x16x32_bf16 v[120:123], v[140:143], v[164:167], v[120:123]
	v_mfma_f32_16x16x32_bf16 v[116:119], v[132:135], v[172:175], v[116:119]
	v_mfma_f32_16x16x32_bf16 v[112:115], v[140:143], v[172:175], v[112:115]
	v_mfma_f32_16x16x32_bf16 v[100:103], v[132:135], v[180:183], v[100:103]
	v_mfma_f32_16x16x32_bf16 v[96:99], v[140:143], v[180:183], v[96:99]
	v_mfma_f32_16x16x32_bf16 v[84:87], v[132:135], v[188:191], v[84:87]
	v_mfma_f32_16x16x32_bf16 v[80:83], v[140:143], v[188:191], v[80:83]
	v_mfma_f32_16x16x32_bf16 v[108:111], v[144:147], v[160:163], v[108:111]
	v_mfma_f32_16x16x32_bf16 v[104:107], v[152:155], v[160:163], v[104:107]
	v_mfma_f32_16x16x32_bf16 v[92:95], v[144:147], v[168:171], v[92:95]
	v_mfma_f32_16x16x32_bf16 v[88:91], v[152:155], v[168:171], v[88:91]
	v_mfma_f32_16x16x32_bf16 v[76:79], v[144:147], v[176:179], v[76:79]
	v_mfma_f32_16x16x32_bf16 v[72:75], v[152:155], v[176:179], v[72:75]
	v_mfma_f32_16x16x32_bf16 v[68:71], v[144:147], v[184:187], v[68:71]
	v_mfma_f32_16x16x32_bf16 v[64:67], v[152:155], v[184:187], v[64:67]
	v_mfma_f32_16x16x32_bf16 v[108:111], v[148:151], v[164:167], v[108:111]
	v_mfma_f32_16x16x32_bf16 v[104:107], v[156:159], v[164:167], v[104:107]
	v_mfma_f32_16x16x32_bf16 v[92:95], v[148:151], v[172:175], v[92:95]
	v_mfma_f32_16x16x32_bf16 v[88:91], v[156:159], v[172:175], v[88:91]
	v_mfma_f32_16x16x32_bf16 v[76:79], v[148:151], v[180:183], v[76:79]
	v_mfma_f32_16x16x32_bf16 v[72:75], v[156:159], v[180:183], v[72:75]
	v_mfma_f32_16x16x32_bf16 v[68:71], v[148:151], v[188:191], v[68:71]
	v_mfma_f32_16x16x32_bf16 v[64:67], v[156:159], v[188:191], v[64:67]
	s_barrier
; #define PG8_STAGE(bufoff, gbase, voff) do { _Pragma("unroll") for (int _i = 0; _i < 2; ++_i) \
;         __builtin_amdgcn_global_load_lds((const unsigned*)((const char*)(gbase) + (voff)[_i]), (LAS unsigned*)(lds + (bufoff) + ldsw + _i * 8192), 16, 0, 0); } while (0)
; #define PG8_LDA(dst, b, h) do { _Pragma("unroll") for (int m = 0; m < 4; ++m) _Pragma("unroll") for (int k = 0; k < 2; ++k) dst[m][k] = *(const LAS bf16x8*)(lds + PG8_SA(b, h) + aoff + m * 2048 + k * 1024); } while (0)
; #define PG8_MMA(ai, bj, At, Bt) do { __builtin_amdgcn_s_setprio(1); _Pragma("unroll") for (int m = 0; m < 4; ++m) _Pragma("unroll") for (int n = 0; n < 2; ++n) _Pragma("unroll") for (int k = 0; k < 2; ++k) \
;         acc[ai][bj][m][n] = __builtin_amdgcn_mfma_f32_16x16x32_bf16(Bt[n][k], At[m][k], acc[ai][bj][m][n], 0, 0, 0); __builtin_amdgcn_s_setprio(0); } while (0)
; #define PG8_WAIT_V(n) asm volatile("s_waitcnt vmcnt(" #n ")" ::: "memory")
; #define PG8_WAIT_L(n) asm volatile("s_waitcnt lgkmcnt(" #n ")" ::: "memory")
; #define PG8_BAR __builtin_amdgcn_s_barrier()
; #define PG8_SCHED __builtin_amdgcn_sched_barrier(0)
; template <class Epi, int AC0, int BC0, int NT0, int AC1, int BC1, int NT1>
; __device__ __forceinline__ void gemm_phase(LAS unsigned char* lds, const Gemm g, const StaticOrder& S, const Epi& E, int tid) {
;     ...
;             PG8_LDA(At, 1, 1); PG8_STAGE(PG8_SB(1, 0), b3, voffB); PG8_STAGE(PG8_SB(1, 1), b3 + hstepB, voffB); PG8_STAGE(PG8_SA(1, 0), a3, voffA);
;             PG8_WAIT_V(8); PG8_WAIT_L(0); PG8_BAR; PG8_MMA(1, 0, At, B0); PG8_MMA(1, 1, At, B1); PG8_BAR; PG8_SCHED;
;         }
	s_add_i32 s18, s51, s27
	v_lshl_add_u64 v[206:207], v[206:207], 0, s[12:13]
	s_mov_b32 m0, s18
	ds_read_b128 v[160:163], v233 offset:49152
	ds_read_b128 v[164:167], v233 offset:50176
	ds_read_b128 v[168:171], v233 offset:51200
	ds_read_b128 v[172:175], v233 offset:52224
	ds_read_b128 v[176:179], v233 offset:53248
	ds_read_b128 v[180:183], v233 offset:54272
	ds_read_b128 v[184:187], v233 offset:55296
	ds_read_b128 v[188:191], v233 offset:56320
	global_load_lds_dwordx4 v[206:207], off
	s_add_i32 m0, s18, 0x2000
	s_add_u32 s18, s22, 0x50080
	v_lshl_add_u64 v[206:207], v[208:209], 0, s[12:13]
	s_addc_u32 s19, s23, 0
	s_add_i32 s22, s52, s27
	global_load_lds_dwordx4 v[206:207], off
	v_lshl_add_u64 v[206:207], s[18:19], 0, v[194:195]
	s_mov_b32 m0, s22
	s_nop 0
	global_load_lds_dwordx4 v[206:207], off
	v_lshl_add_u64 v[206:207], s[18:19], 0, v[198:199]
	s_add_i32 m0, s22, 0x2000
	s_nop 0
	global_load_lds_dwordx4 v[206:207], off
	v_lshl_add_u64 v[206:207], v[210:211], 0, s[12:13]
	s_mov_b32 m0, s34
	s_nop 0
	global_load_lds_dwordx4 v[206:207], off
	v_lshl_add_u64 v[206:207], v[212:213], 0, s[12:13]
	s_mov_b32 m0, s35
	s_nop 0
	global_load_lds_dwordx4 v[206:207], off
	s_waitcnt vmcnt(8)
	s_waitcnt lgkmcnt(0)
	s_barrier
	s_waitcnt lgkmcnt(0)
	v_mfma_f32_16x16x32_bf16 v[60:63], v[128:131], v[160:163], v[60:63]
	v_mfma_f32_16x16x32_bf16 v[56:59], v[136:139], v[160:163], v[56:59]
	v_mfma_f32_16x16x32_bf16 v[52:55], v[128:131], v[168:171], v[52:55]
	v_mfma_f32_16x16x32_bf16 v[48:51], v[136:139], v[168:171], v[48:51]
	v_mfma_f32_16x16x32_bf16 v[36:39], v[128:131], v[176:179], v[36:39]
	v_mfma_f32_16x16x32_bf16 v[32:35], v[136:139], v[176:179], v[32:35]
	v_mfma_f32_16x16x32_bf16 v[20:23], v[128:131], v[184:187], v[20:23]
	v_mfma_f32_16x16x32_bf16 v[16:19], v[136:139], v[184:187], v[16:19]
	v_mfma_f32_16x16x32_bf16 v[60:63], v[132:135], v[164:167], v[60:63]
	v_mfma_f32_16x16x32_bf16 v[56:59], v[140:143], v[164:167], v[56:59]
	v_mfma_f32_16x16x32_bf16 v[52:55], v[132:135], v[172:175], v[52:55]
	v_mfma_f32_16x16x32_bf16 v[48:51], v[140:143], v[172:175], v[48:51]
	v_mfma_f32_16x16x32_bf16 v[36:39], v[132:135], v[180:183], v[36:39]
	v_mfma_f32_16x16x32_bf16 v[32:35], v[140:143], v[180:183], v[32:35]
	v_mfma_f32_16x16x32_bf16 v[20:23], v[132:135], v[188:191], v[20:23]
	v_mfma_f32_16x16x32_bf16 v[16:19], v[140:143], v[188:191], v[16:19]
	v_mfma_f32_16x16x32_bf16 v[44:47], v[144:147], v[160:163], v[44:47]
	v_mfma_f32_16x16x32_bf16 v[40:43], v[152:155], v[160:163], v[40:43]
	v_mfma_f32_16x16x32_bf16 v[28:31], v[144:147], v[168:171], v[28:31]
	v_mfma_f32_16x16x32_bf16 v[24:27], v[152:155], v[168:171], v[24:27]
	v_mfma_f32_16x16x32_bf16 v[12:15], v[144:147], v[176:179], v[12:15]
	v_mfma_f32_16x16x32_bf16 v[8:11], v[152:155], v[176:179], v[8:11]
	v_mfma_f32_16x16x32_bf16 v[4:7], v[144:147], v[184:187], v[4:7]
	v_mfma_f32_16x16x32_bf16 v[0:3], v[152:155], v[184:187], v[0:3]
	v_mfma_f32_16x16x32_bf16 v[44:47], v[148:151], v[164:167], v[44:47]
	v_mfma_f32_16x16x32_bf16 v[40:43], v[156:159], v[164:167], v[40:43]
	v_mfma_f32_16x16x32_bf16 v[28:31], v[148:151], v[172:175], v[28:31]
	v_mfma_f32_16x16x32_bf16 v[24:27], v[156:159], v[172:175], v[24:27]
	v_mfma_f32_16x16x32_bf16 v[12:15], v[148:151], v[180:183], v[12:15]
	v_mfma_f32_16x16x32_bf16 v[8:11], v[156:159], v[180:183], v[8:11]
	v_mfma_f32_16x16x32_bf16 v[4:7], v[148:151], v[188:191], v[4:7]
	v_mfma_f32_16x16x32_bf16 v[0:3], v[156:159], v[188:191], v[0:3]
	s_barrier
	s_add_i32 s50, s50, 2
	s_add_u32 s46, s46, 0x100
	s_addc_u32 s47, s47, 0
	s_cmp_gt_i32 s50, s33
	s_mov_b64 s[18:19], s[20:21]
	s_cbranch_scc0 .LBB0_992
	s_and_b64 vcc, exec, s[10:11]
	s_cbranch_vccz .LBB0_995
	s_barrier
